# baseline (speedup 1.0000x reference)
; template <class ARow, class Epi>
; DI void gemm_tile(const ARow& arow, long a_kstride, const u16* __restrict__ Bt, long ldb, int K, int m0, int n0,
;                   const Epi& epi, char* smem) {
;     ...
;   const int KT = K >> 6;
;   GEMM_STAGE(0, 0);
;   asm volatile("s_waitcnt vmcnt(0)" ::: "memory");
;   __syncthreads();
;   for (int kt = 0; kt < KT; ++kt) {
;     const int cur = kt & 1;
;     if (kt + 1 < KT) GEMM_STAGE(cur ^ 1, kt + 1);
;     const char* sa = smem + cur * 32768 + wm * 64 * 128;
;     const char* sb = smem + cur * 32768 + 16384 + wn * 64 * 128;
; #pragma unroll
;     for (int ks = 0; ks < 2; ++ks) {
;       bf16x8 wf[4], af[4];
; #pragma unroll
;       for (int j = 0; j < 4; ++j) {
;         wf[j] = *(const bf16x8*)(sb + j * 2048 + foff[ks]);
;         af[j] = *(const bf16x8*)(sa + j * 2048 + foff[ks]);
;       }
; #pragma unroll
;       for (int ni = 0; ni < 4; ++ni)
; #pragma unroll
;         for (int mi = 0; mi < 4; ++mi) acc[ni][mi] = __builtin_amdgcn_mfma_f32_16x16x32_bf16(wf[ni], af[mi], acc[ni][mi], 0, 0, 0);
;     }
;     asm volatile("s_waitcnt vmcnt(0)" ::: "memory");
;     __syncthreads();
;   }
.LBB0_217:
	s_and_b32 s6, s1, 0x8000
	s_xor_b32 s7, s6, 0x8000
	v_add_u32_e32 v108, s7, v91
	v_add_u32_e32 v116, s6, v89
	v_or_b32_e32 v117, s6, v90
	v_readfirstlane_b32 s6, v108
	v_add_u32_e32 v109, 0x4000, v108
	v_lshl_add_u64 v[92:93], v[66:67], 0, s[4:5]
	v_add_u32_e32 v110, 0x400, v108
	v_readfirstlane_b32 s7, v109
	s_mov_b32 m0, s6
	v_lshl_add_u64 v[94:95], v[68:69], 0, s[4:5]
	v_add_u32_e32 v111, 0x4400, v108
	v_readfirstlane_b32 s8, v110
	global_load_lds_dwordx4 v[92:93], off
	s_mov_b32 m0, s7
	v_lshl_add_u64 v[96:97], v[70:71], 0, s[4:5]
	v_add_u32_e32 v113, 0x800, v108
	v_readfirstlane_b32 s9, v111
	global_load_lds_dwordx4 v[94:95], off
	s_mov_b32 m0, s8
	v_lshl_add_u64 v[98:99], v[72:73], 0, s[4:5]
	v_add_u32_e32 v114, 0x4800, v108
	v_readfirstlane_b32 s10, v113
	global_load_lds_dwordx4 v[96:97], off
	s_mov_b32 m0, s9
	v_lshl_add_u64 v[100:101], v[74:75], 0, s[4:5]
	v_add_u32_e32 v115, 0xc00, v108
	v_readfirstlane_b32 s11, v114
	global_load_lds_dwordx4 v[98:99], off
	s_mov_b32 m0, s10
	v_lshl_add_u64 v[102:103], v[76:77], 0, s[4:5]
	v_add_u32_e32 v108, 0x4c00, v108
	v_readfirstlane_b32 s12, v115
	global_load_lds_dwordx4 v[100:101], off
	s_mov_b32 m0, s11
	v_lshl_add_u64 v[104:105], v[78:79], 0, s[4:5]
	v_readfirstlane_b32 s13, v108
	global_load_lds_dwordx4 v[102:103], off
	s_mov_b32 m0, s12
	v_lshl_add_u64 v[106:107], v[80:81], 0, s[4:5]
	global_load_lds_dwordx4 v[104:105], off
	s_mov_b32 m0, s13
	v_add_u32_e32 v118, v117, v88
	global_load_lds_dwordx4 v[106:107], off
	v_add_u32_e32 v112, v116, v88
	ds_read_b128 v[92:95], v118 offset:16384
	ds_read_b128 v[96:99], v112
	ds_read_b128 v[100:103], v118 offset:18432
	ds_read_b128 v[104:107], v112 offset:2048
	ds_read_b128 v[108:111], v112 offset:4096
	ds_read_b128 v[112:115], v112 offset:6144
	s_waitcnt lgkmcnt(4)
	v_mfma_f32_16x16x32_bf16 v[60:63], v[92:95], v[96:99], v[60:63]
	v_add_u32_e32 v117, v117, v87
	v_add_u32_e32 v116, v116, v87
	s_add_i32 s1, s1, 0x8000
	s_waitcnt lgkmcnt(2)
	v_mfma_f32_16x16x32_bf16 v[56:59], v[92:95], v[104:107], v[56:59]
	s_add_u32 s4, s4, 0x80
	s_addc_u32 s5, s5, 0
	s_cmpk_eq_i32 s4, 0x780
	s_waitcnt lgkmcnt(1)
	v_mfma_f32_16x16x32_bf16 v[48:51], v[92:95], v[108:111], v[48:51]
	s_waitcnt lgkmcnt(0)
	v_mfma_f32_16x16x32_bf16 v[40:43], v[92:95], v[112:115], v[40:43]
	v_mfma_f32_16x16x32_bf16 v[36:39], v[100:103], v[96:99], v[36:39]
	v_mfma_f32_16x16x32_bf16 v[32:35], v[100:103], v[104:107], v[32:35]
	v_mfma_f32_16x16x32_bf16 v[28:31], v[100:103], v[108:111], v[28:31]
	v_mfma_f32_16x16x32_bf16 v[24:27], v[100:103], v[112:115], v[24:27]
	ds_read_b128 v[92:95], v118 offset:20480
	ds_read_b128 v[100:103], v118 offset:22528
	s_waitcnt lgkmcnt(1)
	v_mfma_f32_16x16x32_bf16 v[20:23], v[92:95], v[96:99], v[20:23]
	v_mfma_f32_16x16x32_bf16 v[16:19], v[92:95], v[104:107], v[16:19]
	v_mfma_f32_16x16x32_bf16 v[12:15], v[92:95], v[108:111], v[12:15]
	v_mfma_f32_16x16x32_bf16 v[8:11], v[92:95], v[112:115], v[8:11]
	ds_read_b128 v[92:95], v117 offset:16384
	s_waitcnt lgkmcnt(1)
	v_mfma_f32_16x16x32_bf16 v[4:7], v[100:103], v[96:99], v[4:7]
	v_mfma_f32_16x16x32_bf16 v[0:3], v[100:103], v[104:107], v[0:3]
	v_mfma_f32_16x16x32_bf16 v[52:55], v[100:103], v[108:111], v[52:55]
	v_mfma_f32_16x16x32_bf16 v[44:47], v[100:103], v[112:115], v[44:47]
	ds_read_b128 v[96:99], v116
	ds_read_b128 v[100:103], v117 offset:18432
	ds_read_b128 v[104:107], v116 offset:2048
	ds_read_b128 v[108:111], v116 offset:4096
	ds_read_b128 v[112:115], v116 offset:6144
	s_waitcnt lgkmcnt(4)
	v_mfma_f32_16x16x32_bf16 v[60:63], v[92:95], v[96:99], v[60:63]
	s_waitcnt lgkmcnt(2)
	v_mfma_f32_16x16x32_bf16 v[56:59], v[92:95], v[104:107], v[56:59]
	s_waitcnt lgkmcnt(1)
	v_mfma_f32_16x16x32_bf16 v[48:51], v[92:95], v[108:111], v[48:51]
	s_waitcnt lgkmcnt(0)
	v_mfma_f32_16x16x32_bf16 v[40:43], v[92:95], v[112:115], v[40:43]
	v_mfma_f32_16x16x32_bf16 v[36:39], v[100:103], v[96:99], v[36:39]
	v_mfma_f32_16x16x32_bf16 v[32:35], v[100:103], v[104:107], v[32:35]
	v_mfma_f32_16x16x32_bf16 v[28:31], v[100:103], v[108:111], v[28:31]
	v_mfma_f32_16x16x32_bf16 v[24:27], v[100:103], v[112:115], v[24:27]
	ds_read_b128 v[92:95], v117 offset:20480
	ds_read_b128 v[100:103], v117 offset:22528
	s_waitcnt lgkmcnt(0)
	s_waitcnt vmcnt(0)
	s_waitcnt vmcnt(0) lgkmcnt(0)
	v_mfma_f32_16x16x32_bf16 v[20:23], v[92:95], v[96:99], v[20:23]
	s_barrier
	v_mfma_f32_16x16x32_bf16 v[16:19], v[92:95], v[104:107], v[16:19]
	v_mfma_f32_16x16x32_bf16 v[12:15], v[92:95], v[108:111], v[12:15]
	v_mfma_f32_16x16x32_bf16 v[8:11], v[92:95], v[112:115], v[8:11]
	v_mfma_f32_16x16x32_bf16 v[4:7], v[100:103], v[96:99], v[4:7]
	v_mfma_f32_16x16x32_bf16 v[0:3], v[100:103], v[104:107], v[0:3]
	v_mfma_f32_16x16x32_bf16 v[52:55], v[100:103], v[108:111], v[52:55]
	v_mfma_f32_16x16x32_bf16 v[44:47], v[100:103], v[112:115], v[44:47]
	s_cbranch_scc0 .LBB0_217
; template <class ARow, class Epi>
; DI void gemm_tile(const ARow& arow, long a_kstride, const u16* __restrict__ Bt, long ldb, int K, int m0, int n0,
;                   const Epi& epi, char* smem) {
;     ...
;         for (int mi = 0; mi < 4; ++mi) acc[ni][mi] = __builtin_amdgcn_mfma_f32_16x16x32_bf16(wf[ni], af[mi], acc[ni][mi], 0, 0, 0);
;     }
;     asm volatile("s_waitcnt vmcnt(0)" ::: "memory");
;     __syncthreads();
;   }
;     ...
;   const int nh = n0 + wn * 64;
;   if (epi.packed(nh)) {
	v_add_u32_e32 v91, v90, v88
	ds_read_b128 v[66:69], v91 offset:49152
	v_add_u32_e32 v88, v89, v88
	ds_read_b128 v[70:73], v88 offset:32768
	ds_read_b128 v[74:77], v88 offset:34816
	ds_read_b128 v[78:81], v88 offset:36864
	ds_read_b128 v[92:95], v88 offset:38912
	v_add_u32_e32 v116, v90, v87
	s_waitcnt lgkmcnt(3)
	v_mfma_f32_16x16x32_bf16 v[60:63], v[66:69], v[70:73], v[60:63]
	s_waitcnt lgkmcnt(2)
	v_mfma_f32_16x16x32_bf16 v[56:59], v[66:69], v[74:77], v[56:59]
	s_waitcnt lgkmcnt(1)
	v_mfma_f32_16x16x32_bf16 v[48:51], v[66:69], v[78:81], v[48:51]
	s_waitcnt lgkmcnt(0)
	v_mfma_f32_16x16x32_bf16 v[40:43], v[66:69], v[92:95], v[40:43]
	ds_read_b128 v[66:69], v91 offset:51200
	s_waitcnt lgkmcnt(0)
	v_mfma_f32_16x16x32_bf16 v[36:39], v[66:69], v[70:73], v[36:39]
	v_mfma_f32_16x16x32_bf16 v[32:35], v[66:69], v[74:77], v[32:35]
	v_mfma_f32_16x16x32_bf16 v[96:99], v[66:69], v[78:81], v[28:31]
	v_mfma_f32_16x16x32_bf16 v[66:69], v[66:69], v[92:95], v[24:27]
	s_nop 2
	ds_read_b128 v[24:27], v91 offset:53248
	s_waitcnt lgkmcnt(0)
	v_mfma_f32_16x16x32_bf16 v[104:107], v[24:27], v[92:95], v[8:11]
	s_nop 2
	ds_read_b128 v[8:11], v91 offset:55296
	v_mfma_f32_16x16x32_bf16 v[20:23], v[24:27], v[70:73], v[20:23]
	s_waitcnt lgkmcnt(0)
	v_mfma_f32_16x16x32_bf16 v[70:73], v[8:11], v[70:73], v[4:7]
	s_nop 2
	ds_read_b128 v[4:7], v116 offset:49152
	v_mfma_f32_16x16x32_bf16 v[100:103], v[24:27], v[78:81], v[12:15]
	s_nop 2
	v_add_u32_e32 v12, v89, v87
	v_mfma_f32_16x16x32_bf16 v[16:19], v[24:27], v[74:77], v[16:19]
	ds_read_b128 v[88:91], v12 offset:32768
	ds_read_b128 v[108:111], v12 offset:36864
	ds_read_b128 v[112:115], v12 offset:38912
	v_mfma_f32_16x16x32_bf16 v[0:3], v[8:11], v[74:77], v[0:3]
	v_mfma_f32_16x16x32_bf16 v[74:77], v[8:11], v[78:81], v[52:55]
	v_mfma_f32_16x16x32_bf16 v[78:81], v[8:11], v[92:95], v[44:47]
	ds_read_b128 v[92:95], v12 offset:34816
	s_waitcnt lgkmcnt(3)
	v_mfma_f32_16x16x32_bf16 v[60:63], v[4:7], v[88:91], v[60:63]
	s_waitcnt lgkmcnt(0)
	v_mfma_f32_16x16x32_bf16 v[44:47], v[4:7], v[92:95], v[56:59]
	v_mfma_f32_16x16x32_bf16 v[28:31], v[4:7], v[108:111], v[48:51]
	v_mfma_f32_16x16x32_bf16 v[12:15], v[4:7], v[112:115], v[40:43]
	ds_read_b128 v[4:7], v116 offset:51200
	s_waitcnt lgkmcnt(0)
	v_mfma_f32_16x16x32_bf16 v[56:59], v[4:7], v[88:91], v[36:39]
	v_mfma_f32_16x16x32_bf16 v[40:43], v[4:7], v[92:95], v[32:35]
	v_mfma_f32_16x16x32_bf16 v[24:27], v[4:7], v[108:111], v[96:99]
	v_mfma_f32_16x16x32_bf16 v[8:11], v[4:7], v[112:115], v[66:69]
	ds_read_b128 v[4:7], v116 offset:53248
	s_nop 0
	ds_read_b128 v[96:99], v116 offset:55296
	s_waitcnt lgkmcnt(0)
	s_waitcnt vmcnt(0)
	s_waitcnt lgkmcnt(0)
	v_mfma_f32_16x16x32_bf16 v[32:35], v[96:99], v[92:95], v[0:3]
	s_nop 2
	v_or_b32_e32 v0, s0, v64
	v_lshl_or_b32 v66, v85, 6, s42
	v_cmp_lt_i32_e32 vcc, s33, v66
	v_mfma_f32_16x16x32_bf16 v[52:55], v[4:7], v[88:91], v[20:23]
	s_barrier
	v_mfma_f32_16x16x32_bf16 v[36:39], v[4:7], v[92:95], v[16:19]
	v_mfma_f32_16x16x32_bf16 v[20:23], v[4:7], v[108:111], v[100:103]
	v_mfma_f32_16x16x32_bf16 v[4:7], v[4:7], v[112:115], v[104:107]
	v_mfma_f32_16x16x32_bf16 v[48:51], v[96:99], v[88:91], v[70:73]
	v_mfma_f32_16x16x32_bf16 v[16:19], v[96:99], v[108:111], v[74:77]
	s_nop 1
	v_lshlrev_b32_e32 v70, 2, v84
	v_or_b32_e32 v64, v66, v70
	v_lshl_add_u32 v74, v86, 6, v0
	v_mfma_f32_16x16x32_bf16 v[0:3], v[96:99], v[112:115], v[78:81]
	s_nop 7
	v_readfirstlane_b32 s99, v66
	s_cmpk_lt_u32 s99, 0x400
	s_cbranch_scc0 .Lfe_A_not_q
; DI unsigned pack2(float a, float b) { v2f f = {a, b}; return __builtin_bit_cast(unsigned, __builtin_convertvector(f, v2bf)); }
; DI float silu_f(float v) { return v / (1.f + fexp(-v)); }
;   DI u32x2 pack(int, int, float a, float b, float c, float d, float&) const { u32x2 v; v.x = pack2(a, b); v.y = pack2(c, d); return v; }
; template <class ARow, class Epi>
; DI void gemm_tile(const ARow& arow, long a_kstride, const u16* __restrict__ Bt, long ldb, int K, int m0, int n0,
;                   const Epi& epi, char* smem) {
;     ...
;   if (epi.packed(nh)) {
; #pragma unroll
;     for (int mi = 0; mi < 4; ++mi) {
;       const int m = m0 + wm * 64 + mi * 16 + fr;
;       float ss = 0.f;
;       u32x2 pk[4];
; #pragma unroll
;       for (int ni = 0; ni < 4; ++ni) pk[ni] = epi.pack(m, nh + ni * 16 + fq * 4, acc[ni][mi][0], acc[ni][mi][1], acc[ni][mi][2], acc[ni][mi][3], ss);
;       epi.finish16(m, nh, ss);
;       u16* rp = epi.rowp(m) + nh;
; #pragma unroll
;       for (int pp = 0; pp < 2; ++pp) {
;         u32x2 a = pk[2 * pp], b = pk[2 * pp + 1];
;         const u32x2 rx = __builtin_amdgcn_permlane16_swap(a.x, b.x, false, false);
;         const u32x2 ry = __builtin_amdgcn_permlane16_swap(a.y, b.y, false, false);
;         const int nst = (fq & 1) ? ((2 * pp + 1) * 16 + (fq - 1) * 4) : ((2 * pp) * 16 + fq * 4);
;         *(u32x4*)(rp + nst) = (u32x4){rx[0], ry[0], rx[1], ry[1]};
;       }
;   DI u32x2 pack(int m, int n, float a, float b, float c, float d, float& ss) const {
;     if (n < q_end) { a *= qscale; b *= qscale; c *= qscale; d *= qscale; }
;     else if (n >= z_start) { a = silu_f(a); b = silu_f(b); c = silu_f(c); d = silu_f(d); }
;     ss += a * a + b * b + c * c + d * d;
;     u32x2 v; v.x = pack2(a, b); v.y = pack2(c, d);
;     return v;
;   }
	s_load_dwordx2 s[100:101], s[56:57], 0x130
	v_and_b32_e32 v152, 1, v84
	v_mul_u32_u24_e32 v152, 12, v152
	v_lshl_add_u32 v152, v84, 2, v152
	v_add_u32_e32 v152, v152, v66
	v_mul_u32_u24_e32 v153, 0xe00, v74
	v_add_u32_e32 v152, v152, v153
	v_lshlrev_b32_e32 v152, 1, v152
	v_add_u32_e32 v153, 0x1c000, v152
	v_add_u32_e32 v154, 0x38000, v152
	v_add_u32_e32 v155, 0x54000, v152
	s_mov_b32 s98, 0x3e38aa3b
	s_nop 3
	v_pk_mul_f32 v[60:61], v[60:61], s[98:99] op_sel_hi:[1,0]
	v_pk_mul_f32 v[62:63], v[62:63], s[98:99] op_sel_hi:[1,0]
	v_pk_mul_f32 v[56:57], v[56:57], s[98:99] op_sel_hi:[1,0]
	v_pk_mul_f32 v[58:59], v[58:59], s[98:99] op_sel_hi:[1,0]
	v_pk_mul_f32 v[52:53], v[52:53], s[98:99] op_sel_hi:[1,0]
	v_pk_mul_f32 v[54:55], v[54:55], s[98:99] op_sel_hi:[1,0]
	v_pk_mul_f32 v[48:49], v[48:49], s[98:99] op_sel_hi:[1,0]
	v_pk_mul_f32 v[50:51], v[50:51], s[98:99] op_sel_hi:[1,0]
	v_cvt_pk_bf16_f32 v120, v60, v61
	v_cvt_pk_bf16_f32 v121, v62, v63
	v_cvt_pk_bf16_f32 v122, v56, v57
	v_cvt_pk_bf16_f32 v123, v58, v59
	v_cvt_pk_bf16_f32 v124, v52, v53
	v_cvt_pk_bf16_f32 v125, v54, v55
	v_cvt_pk_bf16_f32 v126, v48, v49
	v_cvt_pk_bf16_f32 v127, v50, v51
	s_nop 1
	v_permlane16_swap_b32_e32 v120, v122
	v_permlane16_swap_b32_e32 v121, v123
	v_permlane16_swap_b32_e32 v124, v126
	v_permlane16_swap_b32_e32 v125, v127
	s_waitcnt lgkmcnt(0)
	global_store_dwordx4 v152, v[120:123], s[100:101]
	global_store_dwordx4 v152, v[124:127], s[100:101] offset:64
	v_pk_mul_f32 v[44:45], v[44:45], s[98:99] op_sel_hi:[1,0]
	v_pk_mul_f32 v[46:47], v[46:47], s[98:99] op_sel_hi:[1,0]
	v_pk_mul_f32 v[40:41], v[40:41], s[98:99] op_sel_hi:[1,0]
	v_pk_mul_f32 v[42:43], v[42:43], s[98:99] op_sel_hi:[1,0]
	v_pk_mul_f32 v[36:37], v[36:37], s[98:99] op_sel_hi:[1,0]
	v_pk_mul_f32 v[38:39], v[38:39], s[98:99] op_sel_hi:[1,0]
	v_pk_mul_f32 v[32:33], v[32:33], s[98:99] op_sel_hi:[1,0]
	v_pk_mul_f32 v[34:35], v[34:35], s[98:99] op_sel_hi:[1,0]
	v_cvt_pk_bf16_f32 v128, v44, v45
	v_cvt_pk_bf16_f32 v129, v46, v47
	v_cvt_pk_bf16_f32 v130, v40, v41
	v_cvt_pk_bf16_f32 v131, v42, v43
	v_cvt_pk_bf16_f32 v132, v36, v37
	v_cvt_pk_bf16_f32 v133, v38, v39
	v_cvt_pk_bf16_f32 v134, v32, v33
	v_cvt_pk_bf16_f32 v135, v34, v35
	s_nop 1
	v_permlane16_swap_b32_e32 v128, v130
	v_permlane16_swap_b32_e32 v129, v131
	v_permlane16_swap_b32_e32 v132, v134
	v_permlane16_swap_b32_e32 v133, v135
	global_store_dwordx4 v153, v[128:131], s[100:101]
	global_store_dwordx4 v153, v[132:135], s[100:101] offset:64
	v_pk_mul_f32 v[28:29], v[28:29], s[98:99] op_sel_hi:[1,0]
	v_pk_mul_f32 v[30:31], v[30:31], s[98:99] op_sel_hi:[1,0]
	v_pk_mul_f32 v[24:25], v[24:25], s[98:99] op_sel_hi:[1,0]
	v_pk_mul_f32 v[26:27], v[26:27], s[98:99] op_sel_hi:[1,0]
	v_pk_mul_f32 v[20:21], v[20:21], s[98:99] op_sel_hi:[1,0]
	v_pk_mul_f32 v[22:23], v[22:23], s[98:99] op_sel_hi:[1,0]
	v_pk_mul_f32 v[16:17], v[16:17], s[98:99] op_sel_hi:[1,0]
	v_pk_mul_f32 v[18:19], v[18:19], s[98:99] op_sel_hi:[1,0]
	v_cvt_pk_bf16_f32 v136, v28, v29
	v_cvt_pk_bf16_f32 v137, v30, v31
	v_cvt_pk_bf16_f32 v138, v24, v25
	v_cvt_pk_bf16_f32 v139, v26, v27
	v_cvt_pk_bf16_f32 v140, v20, v21
	v_cvt_pk_bf16_f32 v141, v22, v23
	v_cvt_pk_bf16_f32 v142, v16, v17
	v_cvt_pk_bf16_f32 v143, v18, v19
	s_nop 1
	v_permlane16_swap_b32_e32 v136, v138
	v_permlane16_swap_b32_e32 v137, v139
	v_permlane16_swap_b32_e32 v140, v142
	v_permlane16_swap_b32_e32 v141, v143
	global_store_dwordx4 v154, v[136:139], s[100:101]
	global_store_dwordx4 v154, v[140:143], s[100:101] offset:64
	v_pk_mul_f32 v[12:13], v[12:13], s[98:99] op_sel_hi:[1,0]
	v_pk_mul_f32 v[14:15], v[14:15], s[98:99] op_sel_hi:[1,0]
	v_pk_mul_f32 v[8:9], v[8:9], s[98:99] op_sel_hi:[1,0]
	v_pk_mul_f32 v[10:11], v[10:11], s[98:99] op_sel_hi:[1,0]
	v_pk_mul_f32 v[4:5], v[4:5], s[98:99] op_sel_hi:[1,0]
	v_pk_mul_f32 v[6:7], v[6:7], s[98:99] op_sel_hi:[1,0]
	v_pk_mul_f32 v[0:1], v[0:1], s[98:99] op_sel_hi:[1,0]
	v_pk_mul_f32 v[2:3], v[2:3], s[98:99] op_sel_hi:[1,0]
	v_cvt_pk_bf16_f32 v144, v12, v13
	v_cvt_pk_bf16_f32 v145, v14, v15
	v_cvt_pk_bf16_f32 v146, v8, v9
	v_cvt_pk_bf16_f32 v147, v10, v11
	v_cvt_pk_bf16_f32 v148, v4, v5
	v_cvt_pk_bf16_f32 v149, v6, v7
	v_cvt_pk_bf16_f32 v150, v0, v1
	v_cvt_pk_bf16_f32 v151, v2, v3
	s_nop 1
	v_permlane16_swap_b32_e32 v144, v146
	v_permlane16_swap_b32_e32 v145, v147
	v_permlane16_swap_b32_e32 v148, v150
	v_permlane16_swap_b32_e32 v149, v151
	global_store_dwordx4 v155, v[144:147], s[100:101]
	global_store_dwordx4 v155, v[148:151], s[100:101] offset:64
	s_branch .Lfe_join_A

; template <class ARow, class Epi>
; DI void gemm_tile(const ARow& arow, long a_kstride, const u16* __restrict__ Bt, long ldb, int K, int m0, int n0,
;                   const Epi& epi, char* smem) {
;     ...
;   const int KT = K >> 6;
;   GEMM_STAGE(0, 0);
;   asm volatile("s_waitcnt vmcnt(0)" ::: "memory");
;   __syncthreads();
;   for (int kt = 0; kt < KT; ++kt) {
;     const int cur = kt & 1;
;     if (kt + 1 < KT) GEMM_STAGE(cur ^ 1, kt + 1);
;     const char* sa = smem + cur * 32768 + wm * 64 * 128;
;     const char* sb = smem + cur * 32768 + 16384 + wn * 64 * 128;
; #pragma unroll
;     for (int ks = 0; ks < 2; ++ks) {
;       bf16x8 wf[4], af[4];
; #pragma unroll
;       for (int j = 0; j < 4; ++j) {
;         wf[j] = *(const bf16x8*)(sb + j * 2048 + foff[ks]);
;         af[j] = *(const bf16x8*)(sa + j * 2048 + foff[ks]);
;       }
; #pragma unroll
;       for (int ni = 0; ni < 4; ++ni)
; #pragma unroll
;         for (int mi = 0; mi < 4; ++mi) acc[ni][mi] = __builtin_amdgcn_mfma_f32_16x16x32_bf16(wf[ni], af[mi], acc[ni][mi], 0, 0, 0);
;     }
;     asm volatile("s_waitcnt vmcnt(0)" ::: "memory");
;     __syncthreads();
;   }
.LBB0_1045:
	s_and_b32 s20, s19, 0x8000
	s_xor_b32 s21, s20, 0x8000
	v_add_u32_e32 v108, s21, v88
	v_add_u32_e32 v91, s20, v89
	v_or_b32_e32 v116, s20, v90
	v_readfirstlane_b32 s20, v108
	v_add_u32_e32 v109, 0x4000, v108
	v_lshl_add_u64 v[92:93], v[66:67], 0, s[16:17]
	v_add_u32_e32 v110, 0x400, v108
	v_readfirstlane_b32 s21, v109
	s_mov_b32 m0, s20
	v_lshl_add_u64 v[94:95], v[68:69], 0, s[16:17]
	v_add_u32_e32 v111, 0x4400, v108
	v_readfirstlane_b32 s22, v110
	global_load_lds_dwordx4 v[92:93], off
	s_mov_b32 m0, s21
	v_lshl_add_u64 v[96:97], v[70:71], 0, s[16:17]
	v_add_u32_e32 v113, 0x800, v108
	v_readfirstlane_b32 s23, v111
	global_load_lds_dwordx4 v[94:95], off
	s_mov_b32 m0, s22
	v_lshl_add_u64 v[98:99], v[72:73], 0, s[16:17]
	v_add_u32_e32 v114, 0x4800, v108
	v_readfirstlane_b32 s24, v113
	global_load_lds_dwordx4 v[96:97], off
	s_mov_b32 m0, s23
	v_lshl_add_u64 v[100:101], v[74:75], 0, s[16:17]
	v_add_u32_e32 v115, 0xc00, v108
	v_readfirstlane_b32 s25, v114
	global_load_lds_dwordx4 v[98:99], off
	s_mov_b32 m0, s24
	v_lshl_add_u64 v[102:103], v[76:77], 0, s[16:17]
	v_add_u32_e32 v108, 0x4c00, v108
	v_readfirstlane_b32 s26, v115
	global_load_lds_dwordx4 v[100:101], off
	s_mov_b32 m0, s25
	v_lshl_add_u64 v[104:105], v[78:79], 0, s[16:17]
	v_readfirstlane_b32 s27, v108
	global_load_lds_dwordx4 v[102:103], off
	s_mov_b32 m0, s26
	v_lshl_add_u64 v[106:107], v[80:81], 0, s[16:17]
	global_load_lds_dwordx4 v[104:105], off
	s_mov_b32 m0, s27
	v_add_u32_e32 v117, v116, v87
	global_load_lds_dwordx4 v[106:107], off
	v_add_u32_e32 v112, v91, v87
	ds_read_b128 v[92:95], v117 offset:16384
	ds_read_b128 v[96:99], v112
	ds_read_b128 v[100:103], v117 offset:18432
	ds_read_b128 v[104:107], v112 offset:2048
	ds_read_b128 v[108:111], v112 offset:4096
	ds_read_b128 v[112:115], v112 offset:6144
	s_waitcnt lgkmcnt(4)
	v_mfma_f32_16x16x32_bf16 v[60:63], v[92:95], v[96:99], v[60:63]
	v_add_u32_e32 v116, v116, v86
	v_add_u32_e32 v91, v91, v86
	s_add_i32 s19, s19, 0x8000
	s_waitcnt lgkmcnt(2)
	v_mfma_f32_16x16x32_bf16 v[56:59], v[92:95], v[104:107], v[56:59]
	s_add_u32 s16, s16, 0x80
	s_addc_u32 s17, s17, 0
	s_cmpk_lg_i32 s16, 0x780
	s_waitcnt lgkmcnt(1)
	v_mfma_f32_16x16x32_bf16 v[52:55], v[92:95], v[108:111], v[52:55]
	s_waitcnt lgkmcnt(0)
	v_mfma_f32_16x16x32_bf16 v[48:51], v[92:95], v[112:115], v[48:51]
	v_mfma_f32_16x16x32_bf16 v[44:47], v[100:103], v[96:99], v[44:47]
	v_mfma_f32_16x16x32_bf16 v[40:43], v[100:103], v[104:107], v[40:43]
	v_mfma_f32_16x16x32_bf16 v[36:39], v[100:103], v[108:111], v[36:39]
	v_mfma_f32_16x16x32_bf16 v[16:19], v[100:103], v[112:115], v[16:19]
	ds_read_b128 v[92:95], v117 offset:20480
	ds_read_b128 v[100:103], v117 offset:22528
	s_waitcnt lgkmcnt(1)
	v_mfma_f32_16x16x32_bf16 v[32:35], v[92:95], v[96:99], v[32:35]
	v_mfma_f32_16x16x32_bf16 v[12:15], v[92:95], v[104:107], v[12:15]
	v_mfma_f32_16x16x32_bf16 v[8:11], v[92:95], v[108:111], v[8:11]
	v_mfma_f32_16x16x32_bf16 v[4:7], v[92:95], v[112:115], v[4:7]
	ds_read_b128 v[92:95], v116 offset:16384
	s_waitcnt lgkmcnt(1)
	v_mfma_f32_16x16x32_bf16 v[24:27], v[100:103], v[96:99], v[24:27]
	v_mfma_f32_16x16x32_bf16 v[0:3], v[100:103], v[104:107], v[0:3]
	v_mfma_f32_16x16x32_bf16 v[28:31], v[100:103], v[108:111], v[28:31]
	v_mfma_f32_16x16x32_bf16 v[20:23], v[100:103], v[112:115], v[20:23]
	ds_read_b128 v[96:99], v91
	ds_read_b128 v[100:103], v116 offset:18432
	ds_read_b128 v[104:107], v91 offset:2048
	ds_read_b128 v[108:111], v91 offset:4096
	ds_read_b128 v[112:115], v91 offset:6144
	s_waitcnt lgkmcnt(4)
	v_mfma_f32_16x16x32_bf16 v[60:63], v[92:95], v[96:99], v[60:63]
	s_waitcnt lgkmcnt(2)
	v_mfma_f32_16x16x32_bf16 v[56:59], v[92:95], v[104:107], v[56:59]
	s_waitcnt lgkmcnt(1)
	v_mfma_f32_16x16x32_bf16 v[52:55], v[92:95], v[108:111], v[52:55]
	s_waitcnt lgkmcnt(0)
	v_mfma_f32_16x16x32_bf16 v[48:51], v[92:95], v[112:115], v[48:51]
	v_mfma_f32_16x16x32_bf16 v[44:47], v[100:103], v[96:99], v[44:47]
	v_mfma_f32_16x16x32_bf16 v[40:43], v[100:103], v[104:107], v[40:43]
	v_mfma_f32_16x16x32_bf16 v[36:39], v[100:103], v[108:111], v[36:39]
	v_mfma_f32_16x16x32_bf16 v[16:19], v[100:103], v[112:115], v[16:19]
	ds_read_b128 v[92:95], v116 offset:20480
	ds_read_b128 v[100:103], v116 offset:22528
	s_waitcnt lgkmcnt(0)
	s_waitcnt vmcnt(0)
	s_waitcnt vmcnt(0) lgkmcnt(0)
	v_mfma_f32_16x16x32_bf16 v[32:35], v[92:95], v[96:99], v[32:35]
	s_barrier
	v_mfma_f32_16x16x32_bf16 v[12:15], v[92:95], v[104:107], v[12:15]
	v_mfma_f32_16x16x32_bf16 v[8:11], v[92:95], v[108:111], v[8:11]
	v_mfma_f32_16x16x32_bf16 v[4:7], v[92:95], v[112:115], v[4:7]
	v_mfma_f32_16x16x32_bf16 v[24:27], v[100:103], v[96:99], v[24:27]
	v_mfma_f32_16x16x32_bf16 v[0:3], v[100:103], v[104:107], v[0:3]
	v_mfma_f32_16x16x32_bf16 v[28:31], v[100:103], v[108:111], v[28:31]
	v_mfma_f32_16x16x32_bf16 v[20:23], v[100:103], v[112:115], v[20:23]
	s_cbranch_scc1 .LBB0_1045
	v_add_u32_e32 v91, v90, v87
	ds_read_b128 v[66:69], v91 offset:49152
	v_add_u32_e32 v87, v89, v87
	ds_read_b128 v[70:73], v87 offset:32768
	ds_read_b128 v[74:77], v87 offset:34816
	ds_read_b128 v[78:81], v87 offset:36864
	ds_read_b128 v[92:95], v87 offset:38912
	v_add_u32_e32 v120, v89, v86
	v_add_u32_e32 v90, v90, v86
	v_or_b32_e32 v64, s1, v64
	s_waitcnt lgkmcnt(3)
	v_mfma_f32_16x16x32_bf16 v[60:63], v[66:69], v[70:73], v[60:63]
	s_waitcnt lgkmcnt(2)
	v_mfma_f32_16x16x32_bf16 v[56:59], v[66:69], v[74:77], v[56:59]
	s_waitcnt lgkmcnt(1)
	v_mfma_f32_16x16x32_bf16 v[52:55], v[66:69], v[78:81], v[52:55]
	s_waitcnt lgkmcnt(0)
	v_mfma_f32_16x16x32_bf16 v[48:51], v[66:69], v[92:95], v[48:51]
	ds_read_b128 v[66:69], v91 offset:51200
	ds_read_b128 v[86:89], v120 offset:38912
	ds_read_b128 v[96:99], v120 offset:36864
	ds_read_b128 v[100:103], v91 offset:55296
	ds_read_b128 v[104:107], v91 offset:53248
	ds_read_b128 v[108:111], v90 offset:55296
	ds_read_b128 v[112:115], v90 offset:53248
	ds_read_b128 v[116:119], v120 offset:34816
	ds_read_b128 v[120:123], v120 offset:32768
	ds_read_b128 v[124:127], v90 offset:51200
	ds_read_b128 v[128:131], v90 offset:49152
	s_waitcnt lgkmcnt(6)
	v_mfma_f32_16x16x32_bf16 v[32:35], v[104:107], v[70:73], v[32:35]
	s_waitcnt lgkmcnt(0)
	s_waitcnt vmcnt(0)
	s_waitcnt lgkmcnt(0)
	s_barrier
; DI int lbid() { int x = blockIdx.x; asm volatile("" : "+s"(x)); return x; }
;   DI u32x2 pack(int, int, float a, float b, float c, float d, float&) const { u32x2 v; v.x = pack2(a, b); v.y = pack2(c, d); return v; }
; template <class ARow, class Epi>
; DI void gemm_tile(const ARow& arow, long a_kstride, const u16* __restrict__ Bt, long ldb, int K, int m0, int n0,
;                   const Epi& epi, char* smem) {
;     ...
;         for (int mi = 0; mi < 4; ++mi) acc[ni][mi] = __builtin_amdgcn_mfma_f32_16x16x32_bf16(wf[ni], af[mi], acc[ni][mi], 0, 0, 0);
;     }
;     asm volatile("s_waitcnt vmcnt(0)" ::: "memory");
;     __syncthreads();
;   }
;     ...
;   const int nh = n0 + wn * 64;
;   if (epi.packed(nh)) {
; #pragma unroll
;     for (int mi = 0; mi < 4; ++mi) {
;       const int m = m0 + wm * 64 + mi * 16 + fr;
;       float ss = 0.f;
;       u32x2 pk[4];
; #pragma unroll
;       for (int ni = 0; ni < 4; ++ni) pk[ni] = epi.pack(m, nh + ni * 16 + fq * 4, acc[ni][mi][0], acc[ni][mi][1], acc[ni][mi][2], acc[ni][mi][3], ss);
;       epi.finish16(m, nh, ss);
;       u16* rp = epi.rowp(m) + nh;
; #pragma unroll
;       for (int pp = 0; pp < 2; ++pp) {
;         u32x2 a = pk[2 * pp], b = pk[2 * pp + 1];
;         const u32x2 rx = __builtin_amdgcn_permlane16_swap(a.x, b.x, false, false);
;         const u32x2 ry = __builtin_amdgcn_permlane16_swap(a.y, b.y, false, false);
;         const int nst = (fq & 1) ? ((2 * pp + 1) * 16 + (fq - 1) * 4) : ((2 * pp) * 16 + fq * 4);
;         *(u32x4*)(rp + nst) = (u32x4){rx[0], ry[0], rx[1], ry[1]};
;       }
; template <class Epi>
; DI void gemm_phase_plain(const u16* A, long lda, const u16* Bt, long ldb, int M, int N, int K, const Epi& epi, char* smem) {
;     ...
;   for (int t = lbid(); t < nwg; t += gridDim.x) {
;     const int xcd = t & 7, off = t >> 3;
;     const int wg = (xcd < rr ? xcd * (q + 1) : rr * (q + 1) + (xcd - rr) * q) + off;
;     const int nig = 8 * MT, gid = wg / nig, fm = gid * 8, gsz = (NT - fm) < 8 ? (NT - fm) : 8;
;     const int nt = fm + (wg % nig) % gsz, mt = (wg % nig) / gsz;
;     gemm_tile(ar, 64, Bt, ldb, K, mt * 128, nt * 128, epi, smem);
	v_mfma_f32_16x16x32_bf16 v[24:27], v[100:103], v[70:73], v[24:27]
	v_mfma_f32_16x16x32_bf16 v[44:47], v[66:69], v[70:73], v[44:47]
	v_lshl_add_u32 v72, v85, 6, v64
	v_lshl_or_b32 v70, v84, 6, s18
	v_ashrrev_i32_e32 v73, 31, v72
	v_mfma_f32_16x16x32_bf16 v[32:35], v[112:115], v[120:123], v[32:35]
	v_ashrrev_i32_e32 v71, 31, v70
	v_and_b32_e32 v64, 16, v82
	v_lshlrev_b32_e32 v82, 2, v83
	v_mfma_f32_16x16x32_bf16 v[24:27], v[108:111], v[120:123], v[24:27]
	v_cmp_eq_u32_e32 vcc, 0, v64
	s_nop 2
	v_cvt_pk_bf16_f32 v32, v32, v33
	v_cvt_pk_bf16_f32 v33, v34, v35
	v_mfma_f32_16x16x32_bf16 v[60:63], v[128:131], v[120:123], v[60:63]
	v_mfma_f32_16x16x32_bf16 v[44:47], v[124:127], v[120:123], v[44:47]
	v_cvt_pk_bf16_f32 v34, v24, v25
	v_lshlrev_b64 v[24:25], 11, v[72:73]
	s_nop 4
	v_cvt_pk_bf16_f32 v60, v60, v61
	v_cvt_pk_bf16_f32 v61, v62, v63
	v_lshl_add_u64 v[24:25], s[6:7], 0, v[24:25]
	v_cvt_pk_bf16_f32 v62, v44, v45
	v_lshlrev_b64 v[44:45], 1, v[70:71]
	v_cvt_pk_bf16_f32 v63, v46, v47
	v_lshl_add_u64 v[46:47], v[24:25], 0, v[44:45]
	v_add_u32_e32 v24, 12, v82
	v_cndmask_b32_e32 v24, v24, v82, vcc
	v_lshlrev_b32_e32 v64, 1, v24
	v_permlane16_swap_b32_e32 v60, v62
	v_permlane16_swap_b32_e32 v61, v63
	v_lshl_add_u64 v[24:25], v[46:47], 0, v[64:65]
	v_mfma_f32_16x16x32_bf16 v[40:43], v[66:69], v[74:77], v[40:43]
	v_cvt_pk_bf16_f32 v35, v26, v27
	global_store_dwordx4 v[24:25], v[60:63], off
	v_permlane16_swap_b32_e32 v32, v34
	v_mfma_f32_16x16x32_bf16 v[24:27], v[100:103], v[78:81], v[28:31]
	v_mov_b32_e32 v61, v65
	v_permlane16_swap_b32_e32 v33, v35
	s_nop 0
	v_add_u32_e32 v28, 44, v82
	v_or_b32_e32 v29, 32, v82
	v_cndmask_b32_e32 v28, v28, v29, vcc
	v_lshlrev_b32_e32 v60, 1, v28
	v_lshl_add_u64 v[46:47], v[46:47], 0, v[60:61]
	v_mfma_f32_16x16x32_bf16 v[28:31], v[128:131], v[116:119], v[56:59]
	global_store_dwordx4 v[46:47], v[32:35], off
	s_nop 1
	v_mfma_f32_16x16x32_bf16 v[32:35], v[124:127], v[116:119], v[40:43]
	v_mfma_f32_16x16x32_bf16 v[12:15], v[104:107], v[74:77], v[12:15]
	s_nop 2
	v_cvt_pk_bf16_f32 v28, v28, v29
	v_cvt_pk_bf16_f32 v29, v30, v31
	s_nop 1
	v_cvt_pk_bf16_f32 v30, v32, v33
	v_mfma_f32_16x16x32_bf16 v[0:3], v[100:103], v[74:77], v[0:3]
	v_or_b32_e32 v32, 16, v72
	v_ashrrev_i32_e32 v33, 31, v32
	v_lshlrev_b64 v[32:33], 11, v[32:33]
	v_mfma_f32_16x16x32_bf16 v[12:15], v[112:115], v[116:119], v[12:15]
	v_lshl_add_u64 v[40:41], s[6:7], 0, v[32:33]
	v_cvt_pk_bf16_f32 v31, v34, v35
	v_lshl_add_u64 v[40:41], v[40:41], 0, v[44:45]
	v_mfma_f32_16x16x32_bf16 v[0:3], v[108:111], v[116:119], v[0:3]
	v_permlane16_swap_b32_e32 v28, v30
	s_nop 2
	v_cvt_pk_bf16_f32 v12, v12, v13
	v_mfma_f32_16x16x32_bf16 v[8:11], v[104:107], v[78:81], v[8:11]
	v_cvt_pk_bf16_f32 v13, v14, v15
	s_nop 0
	v_cvt_pk_bf16_f32 v14, v0, v1
	v_cvt_pk_bf16_f32 v15, v2, v3
	v_permlane16_swap_b32_e32 v29, v31
	v_lshl_add_u64 v[42:43], v[40:41], 0, v[64:65]
	global_store_dwordx4 v[42:43], v[28:31], off
	v_permlane16_swap_b32_e32 v12, v14
	v_permlane16_swap_b32_e32 v13, v15
	v_lshl_add_u64 v[28:29], v[40:41], 0, v[60:61]
	v_mfma_f32_16x16x32_bf16 v[36:39], v[66:69], v[78:81], v[36:39]
	global_store_dwordx4 v[28:29], v[12:15], off
	v_mfma_f32_16x16x32_bf16 v[8:11], v[112:115], v[96:99], v[8:11]
	s_nop 0
	v_mfma_f32_16x16x32_bf16 v[12:15], v[108:111], v[96:99], v[24:27]
	v_mfma_f32_16x16x32_bf16 v[0:3], v[128:131], v[96:99], v[52:55]
	s_nop 4
	v_cvt_pk_bf16_f32 v8, v8, v9
	v_cvt_pk_bf16_f32 v9, v10, v11
	v_cvt_pk_bf16_f32 v10, v12, v13
	v_mfma_f32_16x16x32_bf16 v[36:39], v[124:127], v[96:99], v[36:39]
	v_or_b32_e32 v12, 32, v72
	v_ashrrev_i32_e32 v13, 31, v12
	v_lshlrev_b64 v[12:13], 11, v[12:13]
	v_mfma_f32_16x16x32_bf16 v[16:19], v[66:69], v[92:95], v[16:19]
	v_lshl_add_u64 v[12:13], s[6:7], 0, v[12:13]
	v_cvt_pk_bf16_f32 v0, v0, v1
	v_cvt_pk_bf16_f32 v1, v2, v3
	v_mfma_f32_16x16x32_bf16 v[4:7], v[104:107], v[92:95], v[4:7]
	v_cvt_pk_bf16_f32 v2, v36, v37
	v_cvt_pk_bf16_f32 v3, v38, v39
	v_lshl_add_u64 v[12:13], v[12:13], 0, v[44:45]
	v_mfma_f32_16x16x32_bf16 v[20:23], v[100:103], v[92:95], v[20:23]
	v_cvt_pk_bf16_f32 v11, v14, v15
	v_permlane16_swap_b32_e32 v0, v2
	v_permlane16_swap_b32_e32 v1, v3
	v_lshl_add_u64 v[14:15], v[12:13], 0, v[64:65]
	global_store_dwordx4 v[14:15], v[0:3], off
	v_permlane16_swap_b32_e32 v8, v10
	v_permlane16_swap_b32_e32 v9, v11
	v_lshl_add_u64 v[0:1], v[12:13], 0, v[60:61]
	v_mfma_f32_16x16x32_bf16 v[32:35], v[128:131], v[86:89], v[48:51]
	global_store_dwordx4 v[0:1], v[8:11], off
	v_mfma_f32_16x16x32_bf16 v[16:19], v[124:127], v[86:89], v[16:19]
	s_nop 0
	v_or_b32_e32 v8, 48, v72
	v_ashrrev_i32_e32 v9, 31, v8
	v_lshlrev_b64 v[8:9], 11, v[8:9]
	v_mfma_f32_16x16x32_bf16 v[4:7], v[112:115], v[86:89], v[4:7]
	v_lshl_add_u64 v[8:9], s[6:7], 0, v[8:9]
	v_cvt_pk_bf16_f32 v0, v32, v33
	v_cvt_pk_bf16_f32 v1, v34, v35
	v_mfma_f32_16x16x32_bf16 v[20:23], v[108:111], v[86:89], v[20:23]
	v_cvt_pk_bf16_f32 v2, v16, v17
	v_cvt_pk_bf16_f32 v3, v18, v19
	v_lshl_add_u64 v[8:9], v[8:9], 0, v[44:45]
	s_nop 0
	v_cvt_pk_bf16_f32 v4, v4, v5
	v_cvt_pk_bf16_f32 v5, v6, v7
	s_nop 1
	v_cvt_pk_bf16_f32 v6, v20, v21
	v_cvt_pk_bf16_f32 v7, v22, v23
	v_permlane16_swap_b32_e32 v0, v2
	v_permlane16_swap_b32_e32 v1, v3
	v_lshl_add_u64 v[10:11], v[8:9], 0, v[64:65]
	global_store_dwordx4 v[10:11], v[0:3], off
	v_permlane16_swap_b32_e32 v4, v6
	v_permlane16_swap_b32_e32 v5, v7
	v_lshl_add_u64 v[0:1], v[8:9], 0, v[60:61]
	global_store_dwordx4 v[0:1], v[4:7], off
	s_load_dword s1, s[10:11], 0x0
	s_waitcnt lgkmcnt(0)
	s_add_i32 s0, s1, s0
	s_cmpk_lt_i32 s0, 0x400
	s_cbranch_scc1 .LBB0_1044

; template <class ARow, class Epi>
; DI void gemm_tile(const ARow& arow, long a_kstride, const u16* __restrict__ Bt, long ldb, int K, int m0, int n0,
;                   const Epi& epi, char* smem) {
;     ...
;   for (int kt = 0; kt < KT; ++kt) {
;     const int cur = kt & 1;
;     if (kt + 1 < KT) GEMM_STAGE(cur ^ 1, kt + 1);
;     const char* sa = smem + cur * 32768 + wm * 64 * 128;
;     const char* sb = smem + cur * 32768 + 16384 + wn * 64 * 128;
; #pragma unroll
;     for (int ks = 0; ks < 2; ++ks) {
;       bf16x8 wf[4], af[4];
; #pragma unroll
;       for (int j = 0; j < 4; ++j) {
;         wf[j] = *(const bf16x8*)(sb + j * 2048 + foff[ks]);
;         af[j] = *(const bf16x8*)(sa + j * 2048 + foff[ks]);
;       }
; #pragma unroll
;       for (int ni = 0; ni < 4; ++ni)
; #pragma unroll
;         for (int mi = 0; mi < 4; ++mi) acc[ni][mi] = __builtin_amdgcn_mfma_f32_16x16x32_bf16(wf[ni], af[mi], acc[ni][mi], 0, 0, 0);
;     }
;     asm volatile("s_waitcnt vmcnt(0)" ::: "memory");
;     __syncthreads();
;   }
.LBB0_1173:
	s_and_b32 s6, s1, 0x8000
	s_xor_b32 s7, s6, 0x8000
	v_add_u32_e32 v108, s7, v91
	v_add_u32_e32 v116, s6, v89
	v_or_b32_e32 v117, s6, v90
	v_readfirstlane_b32 s6, v108
	v_add_u32_e32 v109, 0x4000, v108
	v_lshl_add_u64 v[92:93], v[66:67], 0, s[4:5]
	v_add_u32_e32 v110, 0x400, v108
	v_readfirstlane_b32 s7, v109
	s_mov_b32 m0, s6
	v_lshl_add_u64 v[94:95], v[68:69], 0, s[4:5]
	v_add_u32_e32 v111, 0x4400, v108
	v_readfirstlane_b32 s8, v110
	global_load_lds_dwordx4 v[92:93], off
	s_mov_b32 m0, s7
	v_lshl_add_u64 v[96:97], v[70:71], 0, s[4:5]
	v_add_u32_e32 v113, 0x800, v108
	v_readfirstlane_b32 s9, v111
	global_load_lds_dwordx4 v[94:95], off
	s_mov_b32 m0, s8
	v_lshl_add_u64 v[98:99], v[72:73], 0, s[4:5]
	v_add_u32_e32 v114, 0x4800, v108
	v_readfirstlane_b32 s10, v113
	global_load_lds_dwordx4 v[96:97], off
	s_mov_b32 m0, s9
	v_lshl_add_u64 v[100:101], v[74:75], 0, s[4:5]
	v_add_u32_e32 v115, 0xc00, v108
	v_readfirstlane_b32 s11, v114
	global_load_lds_dwordx4 v[98:99], off
	s_mov_b32 m0, s10
	v_lshl_add_u64 v[102:103], v[76:77], 0, s[4:5]
	v_add_u32_e32 v108, 0x4c00, v108
	v_readfirstlane_b32 s12, v115
	global_load_lds_dwordx4 v[100:101], off
	s_mov_b32 m0, s11
	v_lshl_add_u64 v[104:105], v[78:79], 0, s[4:5]
	v_readfirstlane_b32 s13, v108
	global_load_lds_dwordx4 v[102:103], off
	s_mov_b32 m0, s12
	v_lshl_add_u64 v[106:107], v[80:81], 0, s[4:5]
	global_load_lds_dwordx4 v[104:105], off
	s_mov_b32 m0, s13
	v_add_u32_e32 v118, v117, v88
	global_load_lds_dwordx4 v[106:107], off
	v_add_u32_e32 v112, v116, v88
	ds_read_b128 v[92:95], v118 offset:16384
	ds_read_b128 v[96:99], v112
	ds_read_b128 v[100:103], v118 offset:18432
	ds_read_b128 v[104:107], v112 offset:2048
	ds_read_b128 v[108:111], v112 offset:4096
	ds_read_b128 v[112:115], v112 offset:6144
	s_waitcnt lgkmcnt(4)
	v_mfma_f32_16x16x32_bf16 v[60:63], v[92:95], v[96:99], v[60:63]
	v_add_u32_e32 v117, v117, v87
	v_add_u32_e32 v116, v116, v87
	s_add_i32 s1, s1, 0x8000
	s_waitcnt lgkmcnt(2)
	v_mfma_f32_16x16x32_bf16 v[56:59], v[92:95], v[104:107], v[56:59]
	s_add_u32 s4, s4, 0x80
	s_addc_u32 s5, s5, 0
	s_cmpk_eq_i32 s4, 0x780
	s_waitcnt lgkmcnt(1)
	v_mfma_f32_16x16x32_bf16 v[48:51], v[92:95], v[108:111], v[48:51]
	s_waitcnt lgkmcnt(0)
	v_mfma_f32_16x16x32_bf16 v[40:43], v[92:95], v[112:115], v[40:43]
	v_mfma_f32_16x16x32_bf16 v[36:39], v[100:103], v[96:99], v[36:39]
	v_mfma_f32_16x16x32_bf16 v[32:35], v[100:103], v[104:107], v[32:35]
	v_mfma_f32_16x16x32_bf16 v[28:31], v[100:103], v[108:111], v[28:31]
	v_mfma_f32_16x16x32_bf16 v[24:27], v[100:103], v[112:115], v[24:27]
	ds_read_b128 v[92:95], v118 offset:20480
	ds_read_b128 v[100:103], v118 offset:22528
	s_waitcnt lgkmcnt(1)
	v_mfma_f32_16x16x32_bf16 v[20:23], v[92:95], v[96:99], v[20:23]
	v_mfma_f32_16x16x32_bf16 v[16:19], v[92:95], v[104:107], v[16:19]
	v_mfma_f32_16x16x32_bf16 v[12:15], v[92:95], v[108:111], v[12:15]
	v_mfma_f32_16x16x32_bf16 v[8:11], v[92:95], v[112:115], v[8:11]
	ds_read_b128 v[92:95], v117 offset:16384
	s_waitcnt lgkmcnt(1)
	v_mfma_f32_16x16x32_bf16 v[4:7], v[100:103], v[96:99], v[4:7]
	v_mfma_f32_16x16x32_bf16 v[0:3], v[100:103], v[104:107], v[0:3]
	v_mfma_f32_16x16x32_bf16 v[52:55], v[100:103], v[108:111], v[52:55]
	v_mfma_f32_16x16x32_bf16 v[44:47], v[100:103], v[112:115], v[44:47]
	ds_read_b128 v[96:99], v116
	ds_read_b128 v[100:103], v117 offset:18432
	ds_read_b128 v[104:107], v116 offset:2048
	ds_read_b128 v[108:111], v116 offset:4096
	ds_read_b128 v[112:115], v116 offset:6144
	s_waitcnt lgkmcnt(4)
	v_mfma_f32_16x16x32_bf16 v[60:63], v[92:95], v[96:99], v[60:63]
	s_waitcnt lgkmcnt(2)
	v_mfma_f32_16x16x32_bf16 v[56:59], v[92:95], v[104:107], v[56:59]
	s_waitcnt lgkmcnt(1)
	v_mfma_f32_16x16x32_bf16 v[48:51], v[92:95], v[108:111], v[48:51]
	s_waitcnt lgkmcnt(0)
	v_mfma_f32_16x16x32_bf16 v[40:43], v[92:95], v[112:115], v[40:43]
	v_mfma_f32_16x16x32_bf16 v[36:39], v[100:103], v[96:99], v[36:39]
	v_mfma_f32_16x16x32_bf16 v[32:35], v[100:103], v[104:107], v[32:35]
	v_mfma_f32_16x16x32_bf16 v[28:31], v[100:103], v[108:111], v[28:31]
	v_mfma_f32_16x16x32_bf16 v[24:27], v[100:103], v[112:115], v[24:27]
	ds_read_b128 v[92:95], v117 offset:20480
	ds_read_b128 v[100:103], v117 offset:22528
	s_waitcnt lgkmcnt(0)
	s_waitcnt vmcnt(0)
	s_waitcnt vmcnt(0) lgkmcnt(0)
	v_mfma_f32_16x16x32_bf16 v[20:23], v[92:95], v[96:99], v[20:23]
	s_barrier
	v_mfma_f32_16x16x32_bf16 v[16:19], v[92:95], v[104:107], v[16:19]
	v_mfma_f32_16x16x32_bf16 v[12:15], v[92:95], v[108:111], v[12:15]
	v_mfma_f32_16x16x32_bf16 v[8:11], v[92:95], v[112:115], v[8:11]
	v_mfma_f32_16x16x32_bf16 v[4:7], v[100:103], v[96:99], v[4:7]
	v_mfma_f32_16x16x32_bf16 v[0:3], v[100:103], v[104:107], v[0:3]
	v_mfma_f32_16x16x32_bf16 v[52:55], v[100:103], v[108:111], v[52:55]
	v_mfma_f32_16x16x32_bf16 v[44:47], v[100:103], v[112:115], v[44:47]
	s_cbranch_scc0 .LBB0_1173
;   DI u32x2 pack(int, int, float a, float b, float c, float d, float&) const { u32x2 v; v.x = pack2(a, b); v.y = pack2(c, d); return v; }
; template <class ARow, class Epi>
; DI void gemm_tile(const ARow& arow, long a_kstride, const u16* __restrict__ Bt, long ldb, int K, int m0, int n0,
;                   const Epi& epi, char* smem) {
;     ...
;     for (int ks = 0; ks < 2; ++ks) {
;       bf16x8 wf[4], af[4];
; #pragma unroll
;       for (int j = 0; j < 4; ++j) {
;         wf[j] = *(const bf16x8*)(sb + j * 2048 + foff[ks]);
;         af[j] = *(const bf16x8*)(sa + j * 2048 + foff[ks]);
;       }
; #pragma unroll
;       for (int ni = 0; ni < 4; ++ni)
; #pragma unroll
;         for (int mi = 0; mi < 4; ++mi) acc[ni][mi] = __builtin_amdgcn_mfma_f32_16x16x32_bf16(wf[ni], af[mi], acc[ni][mi], 0, 0, 0);
;     }
;     asm volatile("s_waitcnt vmcnt(0)" ::: "memory");
;     __syncthreads();
;   }
;     ...
;   const int nh = n0 + wn * 64;
;   if (epi.packed(nh)) {
; #pragma unroll
;     for (int mi = 0; mi < 4; ++mi) {
;       const int m = m0 + wm * 64 + mi * 16 + fr;
;       float ss = 0.f;
;       u32x2 pk[4];
; #pragma unroll
;       for (int ni = 0; ni < 4; ++ni) pk[ni] = epi.pack(m, nh + ni * 16 + fq * 4, acc[ni][mi][0], acc[ni][mi][1], acc[ni][mi][2], acc[ni][mi][3], ss);
;       epi.finish16(m, nh, ss);
;       u16* rp = epi.rowp(m) + nh;
; #pragma unroll
;       for (int pp = 0; pp < 2; ++pp) {
;         u32x2 a = pk[2 * pp], b = pk[2 * pp + 1];
;         const u32x2 rx = __builtin_amdgcn_permlane16_swap(a.x, b.x, false, false);
;         const u32x2 ry = __builtin_amdgcn_permlane16_swap(a.y, b.y, false, false);
;         const int nst = (fq & 1) ? ((2 * pp + 1) * 16 + (fq - 1) * 4) : ((2 * pp) * 16 + fq * 4);
;         *(u32x4*)(rp + nst) = (u32x4){rx[0], ry[0], rx[1], ry[1]};
;       }
	v_add_u32_e32 v91, v90, v88
	ds_read_b128 v[66:69], v91 offset:49152
	v_add_u32_e32 v88, v89, v88
	ds_read_b128 v[70:73], v88 offset:32768
	ds_read_b128 v[74:77], v88 offset:34816
	ds_read_b128 v[78:81], v88 offset:36864
	ds_read_b128 v[92:95], v88 offset:38912
	v_add_u32_e32 v116, v90, v87
	s_waitcnt lgkmcnt(3)
	v_mfma_f32_16x16x32_bf16 v[60:63], v[66:69], v[70:73], v[60:63]
	s_waitcnt lgkmcnt(2)
	v_mfma_f32_16x16x32_bf16 v[56:59], v[66:69], v[74:77], v[56:59]
	s_waitcnt lgkmcnt(1)
	v_mfma_f32_16x16x32_bf16 v[48:51], v[66:69], v[78:81], v[48:51]
	s_waitcnt lgkmcnt(0)
	v_mfma_f32_16x16x32_bf16 v[40:43], v[66:69], v[92:95], v[40:43]
	ds_read_b128 v[66:69], v91 offset:51200
	s_waitcnt lgkmcnt(0)
	v_mfma_f32_16x16x32_bf16 v[36:39], v[66:69], v[70:73], v[36:39]
	v_mfma_f32_16x16x32_bf16 v[32:35], v[66:69], v[74:77], v[32:35]
	v_mfma_f32_16x16x32_bf16 v[96:99], v[66:69], v[78:81], v[28:31]
	v_mfma_f32_16x16x32_bf16 v[66:69], v[66:69], v[92:95], v[24:27]
	s_nop 2
	ds_read_b128 v[24:27], v91 offset:53248
	s_waitcnt lgkmcnt(0)
	v_mfma_f32_16x16x32_bf16 v[104:107], v[24:27], v[92:95], v[8:11]
	s_nop 2
	ds_read_b128 v[8:11], v91 offset:55296
	v_mfma_f32_16x16x32_bf16 v[20:23], v[24:27], v[70:73], v[20:23]
	s_waitcnt lgkmcnt(0)
	v_mfma_f32_16x16x32_bf16 v[70:73], v[8:11], v[70:73], v[4:7]
	s_nop 2
	ds_read_b128 v[4:7], v116 offset:49152
	v_mfma_f32_16x16x32_bf16 v[100:103], v[24:27], v[78:81], v[12:15]
	s_nop 2
	v_add_u32_e32 v12, v89, v87
	v_mfma_f32_16x16x32_bf16 v[16:19], v[24:27], v[74:77], v[16:19]
	ds_read_b128 v[88:91], v12 offset:32768
	ds_read_b128 v[108:111], v12 offset:36864
	ds_read_b128 v[112:115], v12 offset:38912
	v_mfma_f32_16x16x32_bf16 v[0:3], v[8:11], v[74:77], v[0:3]
	v_mfma_f32_16x16x32_bf16 v[74:77], v[8:11], v[78:81], v[52:55]
	v_mfma_f32_16x16x32_bf16 v[78:81], v[8:11], v[92:95], v[44:47]
	ds_read_b128 v[92:95], v12 offset:34816
	s_waitcnt lgkmcnt(3)
	v_mfma_f32_16x16x32_bf16 v[60:63], v[4:7], v[88:91], v[60:63]
	s_waitcnt lgkmcnt(0)
	v_mfma_f32_16x16x32_bf16 v[44:47], v[4:7], v[92:95], v[56:59]
	v_mfma_f32_16x16x32_bf16 v[28:31], v[4:7], v[108:111], v[48:51]
	v_mfma_f32_16x16x32_bf16 v[12:15], v[4:7], v[112:115], v[40:43]
	ds_read_b128 v[4:7], v116 offset:51200
	s_waitcnt lgkmcnt(0)
	v_mfma_f32_16x16x32_bf16 v[56:59], v[4:7], v[88:91], v[36:39]
	v_mfma_f32_16x16x32_bf16 v[40:43], v[4:7], v[92:95], v[32:35]
	v_mfma_f32_16x16x32_bf16 v[24:27], v[4:7], v[108:111], v[96:99]
	v_mfma_f32_16x16x32_bf16 v[8:11], v[4:7], v[112:115], v[66:69]
	ds_read_b128 v[4:7], v116 offset:53248
	s_nop 0
	ds_read_b128 v[96:99], v116 offset:55296
	s_waitcnt lgkmcnt(0)
	s_waitcnt vmcnt(0)
	s_waitcnt lgkmcnt(0)
	v_mfma_f32_16x16x32_bf16 v[32:35], v[96:99], v[92:95], v[0:3]
	s_nop 2
	v_or_b32_e32 v0, s0, v64
	v_lshl_add_u32 v66, v86, 6, v0
	v_lshl_or_b32 v68, v85, 6, s38
	v_mfma_f32_16x16x32_bf16 v[52:55], v[4:7], v[88:91], v[20:23]
	v_cmp_lt_i32_e32 vcc, s33, v68
	s_barrier
	v_mfma_f32_16x16x32_bf16 v[36:39], v[4:7], v[92:95], v[16:19]
	v_mfma_f32_16x16x32_bf16 v[20:23], v[4:7], v[108:111], v[100:103]
	v_mfma_f32_16x16x32_bf16 v[4:7], v[4:7], v[112:115], v[104:107]
	v_mfma_f32_16x16x32_bf16 v[48:51], v[96:99], v[88:91], v[70:73]
	v_mfma_f32_16x16x32_bf16 v[16:19], v[96:99], v[108:111], v[74:77]
	s_nop 1
	v_lshlrev_b32_e32 v72, 2, v84
	v_or_b32_e32 v64, v68, v72
	v_mfma_f32_16x16x32_bf16 v[0:3], v[96:99], v[112:115], v[78:81]
	s_nop 7
	v_readfirstlane_b32 s99, v68
	s_cmpk_ge_u32 s99, 0x800
	s_cbranch_scc0 .Lfe_B_not_plain
	s_cmpk_lt_u32 s99, 0xc00
	s_cbranch_scc0 .Lfe_B_not_plain
	s_load_dwordx2 s[100:101], s[56:57], 0x130
	v_and_b32_e32 v152, 1, v84
	v_mul_u32_u24_e32 v152, 12, v152
	v_lshl_add_u32 v152, v84, 2, v152
	v_add_u32_e32 v152, v152, v68
	v_lshl_add_u32 v152, v66, 12, v152
	v_lshlrev_b32_e32 v152, 1, v152
	v_add_u32_e32 v153, 0x20000, v152
	v_add_u32_e32 v154, 0x40000, v152
	v_add_u32_e32 v155, 0x60000, v152
	s_nop 3
	v_cvt_pk_bf16_f32 v120, v60, v61
	v_cvt_pk_bf16_f32 v121, v62, v63
	v_cvt_pk_bf16_f32 v122, v56, v57
	v_cvt_pk_bf16_f32 v123, v58, v59
	v_cvt_pk_bf16_f32 v124, v52, v53
	v_cvt_pk_bf16_f32 v125, v54, v55
	v_cvt_pk_bf16_f32 v126, v48, v49
	v_cvt_pk_bf16_f32 v127, v50, v51
	s_nop 1
	v_permlane16_swap_b32_e32 v120, v122
	v_permlane16_swap_b32_e32 v121, v123
	v_permlane16_swap_b32_e32 v124, v126
	v_permlane16_swap_b32_e32 v125, v127
	s_waitcnt lgkmcnt(0)
	global_store_dwordx4 v152, v[120:123], s[100:101]
	global_store_dwordx4 v152, v[124:127], s[100:101] offset:64
	v_cvt_pk_bf16_f32 v128, v44, v45
	v_cvt_pk_bf16_f32 v129, v46, v47
	v_cvt_pk_bf16_f32 v130, v40, v41
	v_cvt_pk_bf16_f32 v131, v42, v43
	v_cvt_pk_bf16_f32 v132, v36, v37
	v_cvt_pk_bf16_f32 v133, v38, v39
	v_cvt_pk_bf16_f32 v134, v32, v33
	v_cvt_pk_bf16_f32 v135, v34, v35
	s_nop 1
	v_permlane16_swap_b32_e32 v128, v130
	v_permlane16_swap_b32_e32 v129, v131
	v_permlane16_swap_b32_e32 v132, v134
	v_permlane16_swap_b32_e32 v133, v135
	global_store_dwordx4 v153, v[128:131], s[100:101]
	global_store_dwordx4 v153, v[132:135], s[100:101] offset:64
	v_cvt_pk_bf16_f32 v136, v28, v29
	v_cvt_pk_bf16_f32 v137, v30, v31
	v_cvt_pk_bf16_f32 v138, v24, v25
	v_cvt_pk_bf16_f32 v139, v26, v27
	v_cvt_pk_bf16_f32 v140, v20, v21
	v_cvt_pk_bf16_f32 v141, v22, v23
	v_cvt_pk_bf16_f32 v142, v16, v17
	v_cvt_pk_bf16_f32 v143, v18, v19
	s_nop 1
	v_permlane16_swap_b32_e32 v136, v138
	v_permlane16_swap_b32_e32 v137, v139
	v_permlane16_swap_b32_e32 v140, v142
	v_permlane16_swap_b32_e32 v141, v143
	global_store_dwordx4 v154, v[136:139], s[100:101]
	global_store_dwordx4 v154, v[140:143], s[100:101] offset:64
	v_cvt_pk_bf16_f32 v144, v12, v13
	v_cvt_pk_bf16_f32 v145, v14, v15
	v_cvt_pk_bf16_f32 v146, v8, v9
	v_cvt_pk_bf16_f32 v147, v10, v11
	v_cvt_pk_bf16_f32 v148, v4, v5
	v_cvt_pk_bf16_f32 v149, v6, v7
	v_cvt_pk_bf16_f32 v150, v0, v1
	v_cvt_pk_bf16_f32 v151, v2, v3
	s_nop 1
	v_permlane16_swap_b32_e32 v144, v146
	v_permlane16_swap_b32_e32 v145, v147
	v_permlane16_swap_b32_e32 v148, v150
	v_permlane16_swap_b32_e32 v149, v151
	global_store_dwordx4 v155, v[144:147], s[100:101]
	global_store_dwordx4 v155, v[148:151], s[100:101] offset:64
	s_branch .Lfe_join_B

; template <class ARow, class Epi>
; DI void gemm_tile(const ARow& arow, long a_kstride, const u16* __restrict__ Bt, long ldb, int K, int m0, int n0,
;                   const Epi& epi, char* smem) {
;     ...
;   for (int kt = 0; kt < KT; ++kt) {
;     const int cur = kt & 1;
;     if (kt + 1 < KT) GEMM_STAGE(cur ^ 1, kt + 1);
;     const char* sa = smem + cur * 32768 + wm * 64 * 128;
;     const char* sb = smem + cur * 32768 + 16384 + wn * 64 * 128;
; #pragma unroll
;     for (int ks = 0; ks < 2; ++ks) {
;       bf16x8 wf[4], af[4];
; #pragma unroll
;       for (int j = 0; j < 4; ++j) {
;         wf[j] = *(const bf16x8*)(sb + j * 2048 + foff[ks]);
;         af[j] = *(const bf16x8*)(sa + j * 2048 + foff[ks]);
;       }
; #pragma unroll
;       for (int ni = 0; ni < 4; ++ni)
; #pragma unroll
;         for (int mi = 0; mi < 4; ++mi) acc[ni][mi] = __builtin_amdgcn_mfma_f32_16x16x32_bf16(wf[ni], af[mi], acc[ni][mi], 0, 0, 0);
;     }
;     asm volatile("s_waitcnt vmcnt(0)" ::: "memory");
;     __syncthreads();
;   }
.LBB0_1702:
	s_and_b32 s6, s1, 0x8000
	s_xor_b32 s7, s6, 0x8000
	v_add_u32_e32 v108, s7, v90
	v_add_u32_e32 v91, s6, v88
	v_or_b32_e32 v116, s6, v89
	v_readfirstlane_b32 s6, v108
	v_add_u32_e32 v109, 0x4000, v108
	v_lshl_add_u64 v[92:93], v[66:67], 0, s[4:5]
	v_add_u32_e32 v110, 0x400, v108
	v_readfirstlane_b32 s7, v109
	s_mov_b32 m0, s6
	v_lshl_add_u64 v[94:95], v[68:69], 0, s[4:5]
	v_add_u32_e32 v111, 0x4400, v108
	v_readfirstlane_b32 s8, v110
	global_load_lds_dwordx4 v[92:93], off
	s_mov_b32 m0, s7
	v_lshl_add_u64 v[96:97], v[70:71], 0, s[4:5]
	v_add_u32_e32 v113, 0x800, v108
	v_readfirstlane_b32 s9, v111
	global_load_lds_dwordx4 v[94:95], off
	s_mov_b32 m0, s8
	v_lshl_add_u64 v[98:99], v[72:73], 0, s[4:5]
	v_add_u32_e32 v114, 0x4800, v108
	v_readfirstlane_b32 s10, v113
	global_load_lds_dwordx4 v[96:97], off
	s_mov_b32 m0, s9
	v_lshl_add_u64 v[100:101], v[74:75], 0, s[4:5]
	v_add_u32_e32 v115, 0xc00, v108
	v_readfirstlane_b32 s11, v114
	global_load_lds_dwordx4 v[98:99], off
	s_mov_b32 m0, s10
	v_lshl_add_u64 v[102:103], v[76:77], 0, s[4:5]
	v_add_u32_e32 v108, 0x4c00, v108
	v_readfirstlane_b32 s26, v115
	global_load_lds_dwordx4 v[100:101], off
	s_mov_b32 m0, s11
	v_lshl_add_u64 v[104:105], v[78:79], 0, s[4:5]
	v_readfirstlane_b32 s27, v108
	global_load_lds_dwordx4 v[102:103], off
	s_mov_b32 m0, s26
	v_lshl_add_u64 v[106:107], v[80:81], 0, s[4:5]
	global_load_lds_dwordx4 v[104:105], off
	s_mov_b32 m0, s27
	v_add_u32_e32 v117, v116, v87
	global_load_lds_dwordx4 v[106:107], off
	v_add_u32_e32 v112, v91, v87
	ds_read_b128 v[92:95], v117 offset:16384
	ds_read_b128 v[96:99], v112
	ds_read_b128 v[100:103], v117 offset:18432
	ds_read_b128 v[104:107], v112 offset:2048
	ds_read_b128 v[108:111], v112 offset:4096
	ds_read_b128 v[112:115], v112 offset:6144
	s_waitcnt lgkmcnt(4)
	v_mfma_f32_16x16x32_bf16 v[60:63], v[92:95], v[96:99], v[60:63]
	v_add_u32_e32 v116, v116, v86
	v_add_u32_e32 v91, v91, v86
	s_add_i32 s1, s1, 0x8000
	s_waitcnt lgkmcnt(2)
	v_mfma_f32_16x16x32_bf16 v[56:59], v[92:95], v[104:107], v[56:59]
	s_add_u32 s4, s4, 0x80
	s_addc_u32 s5, s5, 0
	s_cmpk_eq_i32 s4, 0x780
	s_waitcnt lgkmcnt(1)
	v_mfma_f32_16x16x32_bf16 v[48:51], v[92:95], v[108:111], v[48:51]
	s_waitcnt lgkmcnt(0)
	v_mfma_f32_16x16x32_bf16 v[40:43], v[92:95], v[112:115], v[40:43]
	v_mfma_f32_16x16x32_bf16 v[36:39], v[100:103], v[96:99], v[36:39]
	v_mfma_f32_16x16x32_bf16 v[32:35], v[100:103], v[104:107], v[32:35]
	v_mfma_f32_16x16x32_bf16 v[28:31], v[100:103], v[108:111], v[28:31]
	v_mfma_f32_16x16x32_bf16 v[24:27], v[100:103], v[112:115], v[24:27]
	ds_read_b128 v[92:95], v117 offset:20480
	ds_read_b128 v[100:103], v117 offset:22528
	s_waitcnt lgkmcnt(1)
	v_mfma_f32_16x16x32_bf16 v[20:23], v[92:95], v[96:99], v[20:23]
	v_mfma_f32_16x16x32_bf16 v[16:19], v[92:95], v[104:107], v[16:19]
	v_mfma_f32_16x16x32_bf16 v[12:15], v[92:95], v[108:111], v[12:15]
	v_mfma_f32_16x16x32_bf16 v[8:11], v[92:95], v[112:115], v[8:11]
	ds_read_b128 v[92:95], v116 offset:16384
	s_waitcnt lgkmcnt(1)
	v_mfma_f32_16x16x32_bf16 v[4:7], v[100:103], v[96:99], v[4:7]
	v_mfma_f32_16x16x32_bf16 v[0:3], v[100:103], v[104:107], v[0:3]
	v_mfma_f32_16x16x32_bf16 v[52:55], v[100:103], v[108:111], v[52:55]
	v_mfma_f32_16x16x32_bf16 v[44:47], v[100:103], v[112:115], v[44:47]
	ds_read_b128 v[96:99], v91
	ds_read_b128 v[100:103], v116 offset:18432
	ds_read_b128 v[104:107], v91 offset:2048
	ds_read_b128 v[108:111], v91 offset:4096
	ds_read_b128 v[112:115], v91 offset:6144
	s_waitcnt lgkmcnt(4)
	v_mfma_f32_16x16x32_bf16 v[60:63], v[92:95], v[96:99], v[60:63]
	s_waitcnt lgkmcnt(2)
	v_mfma_f32_16x16x32_bf16 v[56:59], v[92:95], v[104:107], v[56:59]
	s_waitcnt lgkmcnt(1)
	v_mfma_f32_16x16x32_bf16 v[48:51], v[92:95], v[108:111], v[48:51]
	s_waitcnt lgkmcnt(0)
	v_mfma_f32_16x16x32_bf16 v[40:43], v[92:95], v[112:115], v[40:43]
	v_mfma_f32_16x16x32_bf16 v[36:39], v[100:103], v[96:99], v[36:39]
	v_mfma_f32_16x16x32_bf16 v[32:35], v[100:103], v[104:107], v[32:35]
	v_mfma_f32_16x16x32_bf16 v[28:31], v[100:103], v[108:111], v[28:31]
	v_mfma_f32_16x16x32_bf16 v[24:27], v[100:103], v[112:115], v[24:27]
	ds_read_b128 v[92:95], v116 offset:20480
	ds_read_b128 v[100:103], v116 offset:22528
	s_waitcnt lgkmcnt(0)
	s_waitcnt vmcnt(0)
	s_waitcnt vmcnt(0) lgkmcnt(0)
	v_mfma_f32_16x16x32_bf16 v[20:23], v[92:95], v[96:99], v[20:23]
	s_barrier
	v_mfma_f32_16x16x32_bf16 v[16:19], v[92:95], v[104:107], v[16:19]
	v_mfma_f32_16x16x32_bf16 v[12:15], v[92:95], v[108:111], v[12:15]
	v_mfma_f32_16x16x32_bf16 v[8:11], v[92:95], v[112:115], v[8:11]
	v_mfma_f32_16x16x32_bf16 v[4:7], v[100:103], v[96:99], v[4:7]
	v_mfma_f32_16x16x32_bf16 v[0:3], v[100:103], v[104:107], v[0:3]
	v_mfma_f32_16x16x32_bf16 v[52:55], v[100:103], v[108:111], v[52:55]
	v_mfma_f32_16x16x32_bf16 v[44:47], v[100:103], v[112:115], v[44:47]
	s_cbranch_scc0 .LBB0_1702
;   DI u32x2 pack(int, int, float a, float b, float c, float d, float&) const { u32x2 v; v.x = pack2(a, b); v.y = pack2(c, d); return v; }
; template <class ARow, class Epi>
; DI void gemm_tile(const ARow& arow, long a_kstride, const u16* __restrict__ Bt, long ldb, int K, int m0, int n0,
;                   const Epi& epi, char* smem) {
;     ...
;     for (int ks = 0; ks < 2; ++ks) {
;       bf16x8 wf[4], af[4];
; #pragma unroll
;       for (int j = 0; j < 4; ++j) {
;         wf[j] = *(const bf16x8*)(sb + j * 2048 + foff[ks]);
;         af[j] = *(const bf16x8*)(sa + j * 2048 + foff[ks]);
;       }
; #pragma unroll
;       for (int ni = 0; ni < 4; ++ni)
; #pragma unroll
;         for (int mi = 0; mi < 4; ++mi) acc[ni][mi] = __builtin_amdgcn_mfma_f32_16x16x32_bf16(wf[ni], af[mi], acc[ni][mi], 0, 0, 0);
;     }
;     asm volatile("s_waitcnt vmcnt(0)" ::: "memory");
;     __syncthreads();
;   }
;     ...
;   const int nh = n0 + wn * 64;
;   if (epi.packed(nh)) {
; #pragma unroll
;     for (int mi = 0; mi < 4; ++mi) {
;       const int m = m0 + wm * 64 + mi * 16 + fr;
;       float ss = 0.f;
;       u32x2 pk[4];
; #pragma unroll
;       for (int ni = 0; ni < 4; ++ni) pk[ni] = epi.pack(m, nh + ni * 16 + fq * 4, acc[ni][mi][0], acc[ni][mi][1], acc[ni][mi][2], acc[ni][mi][3], ss);
;       epi.finish16(m, nh, ss);
;       u16* rp = epi.rowp(m) + nh;
; #pragma unroll
;       for (int pp = 0; pp < 2; ++pp) {
;         u32x2 a = pk[2 * pp], b = pk[2 * pp + 1];
;         const u32x2 rx = __builtin_amdgcn_permlane16_swap(a.x, b.x, false, false);
;         const u32x2 ry = __builtin_amdgcn_permlane16_swap(a.y, b.y, false, false);
;         const int nst = (fq & 1) ? ((2 * pp + 1) * 16 + (fq - 1) * 4) : ((2 * pp) * 16 + fq * 4);
;         *(u32x4*)(rp + nst) = (u32x4){rx[0], ry[0], rx[1], ry[1]};
;       }
	v_add_u32_e32 v106, v89, v87
	ds_read_b128 v[66:69], v106 offset:49152
	v_add_u32_e32 v87, v88, v87
	ds_read_b128 v[70:73], v87 offset:32768
	ds_read_b128 v[74:77], v87 offset:34816
	ds_read_b128 v[78:81], v87 offset:36864
	ds_read_b128 v[90:93], v87 offset:38912
	v_add_u32_e32 v114, v89, v86
	s_waitcnt lgkmcnt(3)
	v_mfma_f32_16x16x32_bf16 v[60:63], v[66:69], v[70:73], v[60:63]
	s_waitcnt lgkmcnt(2)
	v_mfma_f32_16x16x32_bf16 v[56:59], v[66:69], v[74:77], v[56:59]
	s_waitcnt lgkmcnt(1)
	v_mfma_f32_16x16x32_bf16 v[48:51], v[66:69], v[78:81], v[48:51]
	s_waitcnt lgkmcnt(0)
	v_mfma_f32_16x16x32_bf16 v[40:43], v[66:69], v[90:93], v[40:43]
	ds_read_b128 v[66:69], v106 offset:51200
	s_waitcnt lgkmcnt(0)
	v_mfma_f32_16x16x32_bf16 v[36:39], v[66:69], v[70:73], v[36:39]
	v_mfma_f32_16x16x32_bf16 v[32:35], v[66:69], v[74:77], v[32:35]
	v_mfma_f32_16x16x32_bf16 v[94:97], v[66:69], v[78:81], v[28:31]
	v_mfma_f32_16x16x32_bf16 v[66:69], v[66:69], v[90:93], v[24:27]
	s_nop 2
	ds_read_b128 v[24:27], v106 offset:53248
	s_waitcnt lgkmcnt(0)
	v_mfma_f32_16x16x32_bf16 v[102:105], v[24:27], v[90:93], v[8:11]
	s_nop 2
	ds_read_b128 v[8:11], v106 offset:55296
	v_mfma_f32_16x16x32_bf16 v[20:23], v[24:27], v[70:73], v[20:23]
	s_waitcnt lgkmcnt(0)
	v_mfma_f32_16x16x32_bf16 v[70:73], v[8:11], v[70:73], v[4:7]
	s_nop 2
	ds_read_b128 v[4:7], v114 offset:49152
	v_mfma_f32_16x16x32_bf16 v[98:101], v[24:27], v[78:81], v[12:15]
	s_nop 2
	v_add_u32_e32 v12, v88, v86
	v_mfma_f32_16x16x32_bf16 v[16:19], v[24:27], v[74:77], v[16:19]
	ds_read_b128 v[86:89], v12 offset:32768
	ds_read_b128 v[106:109], v12 offset:36864
	ds_read_b128 v[110:113], v12 offset:38912
	v_mfma_f32_16x16x32_bf16 v[0:3], v[8:11], v[74:77], v[0:3]
	v_mfma_f32_16x16x32_bf16 v[74:77], v[8:11], v[78:81], v[52:55]
	v_mfma_f32_16x16x32_bf16 v[78:81], v[8:11], v[90:93], v[44:47]
	ds_read_b128 v[90:93], v12 offset:34816
	s_waitcnt lgkmcnt(3)
	v_mfma_f32_16x16x32_bf16 v[60:63], v[4:7], v[86:89], v[60:63]
	s_waitcnt lgkmcnt(0)
	v_mfma_f32_16x16x32_bf16 v[44:47], v[4:7], v[90:93], v[56:59]
	v_mfma_f32_16x16x32_bf16 v[28:31], v[4:7], v[106:109], v[48:51]
	v_mfma_f32_16x16x32_bf16 v[12:15], v[4:7], v[110:113], v[40:43]
	ds_read_b128 v[4:7], v114 offset:51200
	s_waitcnt lgkmcnt(0)
	v_mfma_f32_16x16x32_bf16 v[56:59], v[4:7], v[86:89], v[36:39]
	v_mfma_f32_16x16x32_bf16 v[40:43], v[4:7], v[90:93], v[32:35]
	v_mfma_f32_16x16x32_bf16 v[24:27], v[4:7], v[106:109], v[94:97]
	v_mfma_f32_16x16x32_bf16 v[8:11], v[4:7], v[110:113], v[66:69]
	ds_read_b128 v[4:7], v114 offset:53248
	s_nop 0
	ds_read_b128 v[94:97], v114 offset:55296
	s_waitcnt lgkmcnt(0)
	s_waitcnt vmcnt(0)
	s_waitcnt lgkmcnt(0)
	v_mfma_f32_16x16x32_bf16 v[32:35], v[94:97], v[90:93], v[0:3]
	s_nop 2
	v_or_b32_e32 v0, s0, v64
	v_lshl_or_b32 v66, v84, 6, s35
	v_lshlrev_b32_e32 v68, 2, v83
	v_mfma_f32_16x16x32_bf16 v[52:55], v[4:7], v[86:89], v[20:23]
	v_cmp_lt_i32_e32 vcc, s30, v66
	v_or_b32_e32 v64, v66, v68
	v_mfma_f32_16x16x32_bf16 v[36:39], v[4:7], v[90:93], v[16:19]
	s_barrier
	v_mfma_f32_16x16x32_bf16 v[20:23], v[4:7], v[106:109], v[98:101]
	v_mfma_f32_16x16x32_bf16 v[4:7], v[4:7], v[110:113], v[102:105]
	v_mfma_f32_16x16x32_bf16 v[48:51], v[94:97], v[86:89], v[70:73]
	v_mfma_f32_16x16x32_bf16 v[16:19], v[94:97], v[106:109], v[74:77]
	s_nop 2
	v_lshl_add_u32 v74, v85, 6, v0
	v_mfma_f32_16x16x32_bf16 v[0:3], v[94:97], v[110:113], v[78:81]
	s_nop 7
	v_readfirstlane_b32 s99, v66
	s_cmpk_ge_u32 s99, 0x300
	s_cbranch_scc0 .Lfe_C_not_plain
	s_cmpk_lt_u32 s99, 0xa00
	s_cbranch_scc0 .Lfe_C_not_plain
	s_load_dwordx2 s[100:101], s[56:57], 0x130
	v_and_b32_e32 v152, 1, v83
	v_mul_u32_u24_e32 v152, 12, v152
	v_lshl_add_u32 v152, v83, 2, v152
	v_add_u32_e32 v152, v152, v66
	v_mul_u32_u24_e32 v153, 0xe00, v74
	v_add_u32_e32 v152, v152, v153
	v_lshlrev_b32_e32 v152, 1, v152
	v_add_u32_e32 v153, 0x1c000, v152
	v_add_u32_e32 v154, 0x38000, v152
	v_add_u32_e32 v155, 0x54000, v152
	s_nop 3
	v_cvt_pk_bf16_f32 v120, v60, v61
	v_cvt_pk_bf16_f32 v121, v62, v63
	v_cvt_pk_bf16_f32 v122, v56, v57
	v_cvt_pk_bf16_f32 v123, v58, v59
	v_cvt_pk_bf16_f32 v124, v52, v53
	v_cvt_pk_bf16_f32 v125, v54, v55
	v_cvt_pk_bf16_f32 v126, v48, v49
	v_cvt_pk_bf16_f32 v127, v50, v51
	s_nop 1
	v_permlane16_swap_b32_e32 v120, v122
	v_permlane16_swap_b32_e32 v121, v123
	v_permlane16_swap_b32_e32 v124, v126
	v_permlane16_swap_b32_e32 v125, v127
	s_waitcnt lgkmcnt(0)
	global_store_dwordx4 v152, v[120:123], s[100:101]
	global_store_dwordx4 v152, v[124:127], s[100:101] offset:64
	v_cvt_pk_bf16_f32 v128, v44, v45
	v_cvt_pk_bf16_f32 v129, v46, v47
	v_cvt_pk_bf16_f32 v130, v40, v41
	v_cvt_pk_bf16_f32 v131, v42, v43
	v_cvt_pk_bf16_f32 v132, v36, v37
	v_cvt_pk_bf16_f32 v133, v38, v39
	v_cvt_pk_bf16_f32 v134, v32, v33
	v_cvt_pk_bf16_f32 v135, v34, v35
	s_nop 1
	v_permlane16_swap_b32_e32 v128, v130
	v_permlane16_swap_b32_e32 v129, v131
	v_permlane16_swap_b32_e32 v132, v134
	v_permlane16_swap_b32_e32 v133, v135
	global_store_dwordx4 v153, v[128:131], s[100:101]
	global_store_dwordx4 v153, v[132:135], s[100:101] offset:64
	v_cvt_pk_bf16_f32 v136, v28, v29
	v_cvt_pk_bf16_f32 v137, v30, v31
	v_cvt_pk_bf16_f32 v138, v24, v25
	v_cvt_pk_bf16_f32 v139, v26, v27
	v_cvt_pk_bf16_f32 v140, v20, v21
	v_cvt_pk_bf16_f32 v141, v22, v23
	v_cvt_pk_bf16_f32 v142, v16, v17
	v_cvt_pk_bf16_f32 v143, v18, v19
	s_nop 1
	v_permlane16_swap_b32_e32 v136, v138
	v_permlane16_swap_b32_e32 v137, v139
	v_permlane16_swap_b32_e32 v140, v142
	v_permlane16_swap_b32_e32 v141, v143
	global_store_dwordx4 v154, v[136:139], s[100:101]
	global_store_dwordx4 v154, v[140:143], s[100:101] offset:64
	v_cvt_pk_bf16_f32 v144, v12, v13
	v_cvt_pk_bf16_f32 v145, v14, v15
	v_cvt_pk_bf16_f32 v146, v8, v9
	v_cvt_pk_bf16_f32 v147, v10, v11
	v_cvt_pk_bf16_f32 v148, v4, v5
	v_cvt_pk_bf16_f32 v149, v6, v7
	v_cvt_pk_bf16_f32 v150, v0, v1
	v_cvt_pk_bf16_f32 v151, v2, v3
	s_nop 1
	v_permlane16_swap_b32_e32 v144, v146
	v_permlane16_swap_b32_e32 v145, v147
	v_permlane16_swap_b32_e32 v148, v150
	v_permlane16_swap_b32_e32 v149, v151
	global_store_dwordx4 v155, v[144:147], s[100:101]
	global_store_dwordx4 v155, v[148:151], s[100:101] offset:64
	s_branch .Lfe_join_C

; template <class ARow, class Epi>
; DI void gemm_tile(const ARow& arow, long a_kstride, const u16* __restrict__ Bt, long ldb, int K, int m0, int n0,
;                   const Epi& epi, char* smem) {
;     ...
;   for (int kt = 0; kt < KT; ++kt) {
;     const int cur = kt & 1;
;     if (kt + 1 < KT) GEMM_STAGE(cur ^ 1, kt + 1);
;     const char* sa = smem + cur * 32768 + wm * 64 * 128;
;     const char* sb = smem + cur * 32768 + 16384 + wn * 64 * 128;
; #pragma unroll
;     for (int ks = 0; ks < 2; ++ks) {
;       bf16x8 wf[4], af[4];
; #pragma unroll
;       for (int j = 0; j < 4; ++j) {
;         wf[j] = *(const bf16x8*)(sb + j * 2048 + foff[ks]);
;         af[j] = *(const bf16x8*)(sa + j * 2048 + foff[ks]);
;       }
; #pragma unroll
;       for (int ni = 0; ni < 4; ++ni)
; #pragma unroll
;         for (int mi = 0; mi < 4; ++mi) acc[ni][mi] = __builtin_amdgcn_mfma_f32_16x16x32_bf16(wf[ni], af[mi], acc[ni][mi], 0, 0, 0);
;     }
;     asm volatile("s_waitcnt vmcnt(0)" ::: "memory");
;     __syncthreads();
;   }
.LBB0_2314:
	s_and_b32 s6, s1, 0x8000
	s_xor_b32 s7, s6, 0x8000
	v_add_u32_e32 v108, s7, v90
	v_add_u32_e32 v91, s6, v88
	v_or_b32_e32 v116, s6, v89
	v_readfirstlane_b32 s6, v108
	v_add_u32_e32 v109, 0x4000, v108
	v_lshl_add_u64 v[92:93], v[66:67], 0, s[4:5]
	v_add_u32_e32 v110, 0x400, v108
	v_readfirstlane_b32 s7, v109
	s_mov_b32 m0, s6
	v_lshl_add_u64 v[94:95], v[68:69], 0, s[4:5]
	v_add_u32_e32 v111, 0x4400, v108
	v_readfirstlane_b32 s8, v110
	global_load_lds_dwordx4 v[92:93], off
	s_mov_b32 m0, s7
	v_lshl_add_u64 v[96:97], v[70:71], 0, s[4:5]
	v_add_u32_e32 v113, 0x800, v108
	v_readfirstlane_b32 s9, v111
	global_load_lds_dwordx4 v[94:95], off
	s_mov_b32 m0, s8
	v_lshl_add_u64 v[98:99], v[72:73], 0, s[4:5]
	v_add_u32_e32 v114, 0x4800, v108
	v_readfirstlane_b32 s10, v113
	global_load_lds_dwordx4 v[96:97], off
	s_mov_b32 m0, s9
	v_lshl_add_u64 v[100:101], v[74:75], 0, s[4:5]
	v_add_u32_e32 v115, 0xc00, v108
	v_readfirstlane_b32 s11, v114
	global_load_lds_dwordx4 v[98:99], off
	s_mov_b32 m0, s10
	v_lshl_add_u64 v[102:103], v[76:77], 0, s[4:5]
	v_add_u32_e32 v108, 0x4c00, v108
	v_readfirstlane_b32 s26, v115
	global_load_lds_dwordx4 v[100:101], off
	s_mov_b32 m0, s11
	v_lshl_add_u64 v[104:105], v[78:79], 0, s[4:5]
	v_readfirstlane_b32 s27, v108
	global_load_lds_dwordx4 v[102:103], off
	s_mov_b32 m0, s26
	v_lshl_add_u64 v[106:107], v[80:81], 0, s[4:5]
	global_load_lds_dwordx4 v[104:105], off
	s_mov_b32 m0, s27
	v_add_u32_e32 v117, v116, v87
	global_load_lds_dwordx4 v[106:107], off
	v_add_u32_e32 v112, v91, v87
	ds_read_b128 v[92:95], v117 offset:16384
	ds_read_b128 v[96:99], v112
	ds_read_b128 v[100:103], v117 offset:18432
	ds_read_b128 v[104:107], v112 offset:2048
	ds_read_b128 v[108:111], v112 offset:4096
	ds_read_b128 v[112:115], v112 offset:6144
	s_waitcnt lgkmcnt(4)
	v_mfma_f32_16x16x32_bf16 v[60:63], v[92:95], v[96:99], v[60:63]
	v_add_u32_e32 v116, v116, v86
	v_add_u32_e32 v91, v91, v86
	s_add_i32 s1, s1, 0x8000
	s_waitcnt lgkmcnt(2)
	v_mfma_f32_16x16x32_bf16 v[56:59], v[92:95], v[104:107], v[56:59]
	s_add_u32 s4, s4, 0x80
	s_addc_u32 s5, s5, 0
	s_cmpk_eq_i32 s4, 0x780
	s_waitcnt lgkmcnt(1)
	v_mfma_f32_16x16x32_bf16 v[48:51], v[92:95], v[108:111], v[48:51]
	s_waitcnt lgkmcnt(0)
	v_mfma_f32_16x16x32_bf16 v[40:43], v[92:95], v[112:115], v[40:43]
	v_mfma_f32_16x16x32_bf16 v[36:39], v[100:103], v[96:99], v[36:39]
	v_mfma_f32_16x16x32_bf16 v[32:35], v[100:103], v[104:107], v[32:35]
	v_mfma_f32_16x16x32_bf16 v[28:31], v[100:103], v[108:111], v[28:31]
	v_mfma_f32_16x16x32_bf16 v[24:27], v[100:103], v[112:115], v[24:27]
	ds_read_b128 v[92:95], v117 offset:20480
	ds_read_b128 v[100:103], v117 offset:22528
	s_waitcnt lgkmcnt(1)
	v_mfma_f32_16x16x32_bf16 v[20:23], v[92:95], v[96:99], v[20:23]
	v_mfma_f32_16x16x32_bf16 v[16:19], v[92:95], v[104:107], v[16:19]
	v_mfma_f32_16x16x32_bf16 v[12:15], v[92:95], v[108:111], v[12:15]
	v_mfma_f32_16x16x32_bf16 v[8:11], v[92:95], v[112:115], v[8:11]
	ds_read_b128 v[92:95], v116 offset:16384
	s_waitcnt lgkmcnt(1)
	v_mfma_f32_16x16x32_bf16 v[4:7], v[100:103], v[96:99], v[4:7]
	v_mfma_f32_16x16x32_bf16 v[0:3], v[100:103], v[104:107], v[0:3]
	v_mfma_f32_16x16x32_bf16 v[52:55], v[100:103], v[108:111], v[52:55]
	v_mfma_f32_16x16x32_bf16 v[44:47], v[100:103], v[112:115], v[44:47]
	ds_read_b128 v[96:99], v91
	ds_read_b128 v[100:103], v116 offset:18432
	ds_read_b128 v[104:107], v91 offset:2048
	ds_read_b128 v[108:111], v91 offset:4096
	ds_read_b128 v[112:115], v91 offset:6144
	s_waitcnt lgkmcnt(4)
	v_mfma_f32_16x16x32_bf16 v[60:63], v[92:95], v[96:99], v[60:63]
	s_waitcnt lgkmcnt(2)
	v_mfma_f32_16x16x32_bf16 v[56:59], v[92:95], v[104:107], v[56:59]
	s_waitcnt lgkmcnt(1)
	v_mfma_f32_16x16x32_bf16 v[48:51], v[92:95], v[108:111], v[48:51]
	s_waitcnt lgkmcnt(0)
	v_mfma_f32_16x16x32_bf16 v[40:43], v[92:95], v[112:115], v[40:43]
	v_mfma_f32_16x16x32_bf16 v[36:39], v[100:103], v[96:99], v[36:39]
	v_mfma_f32_16x16x32_bf16 v[32:35], v[100:103], v[104:107], v[32:35]
	v_mfma_f32_16x16x32_bf16 v[28:31], v[100:103], v[108:111], v[28:31]
	v_mfma_f32_16x16x32_bf16 v[24:27], v[100:103], v[112:115], v[24:27]
	ds_read_b128 v[92:95], v116 offset:20480
	ds_read_b128 v[100:103], v116 offset:22528
	s_waitcnt lgkmcnt(0)
	s_waitcnt vmcnt(0)
	s_waitcnt vmcnt(0) lgkmcnt(0)
	v_mfma_f32_16x16x32_bf16 v[20:23], v[92:95], v[96:99], v[20:23]
	s_barrier
	v_mfma_f32_16x16x32_bf16 v[16:19], v[92:95], v[104:107], v[16:19]
	v_mfma_f32_16x16x32_bf16 v[12:15], v[92:95], v[108:111], v[12:15]
	v_mfma_f32_16x16x32_bf16 v[8:11], v[92:95], v[112:115], v[8:11]
	v_mfma_f32_16x16x32_bf16 v[4:7], v[100:103], v[96:99], v[4:7]
	v_mfma_f32_16x16x32_bf16 v[0:3], v[100:103], v[104:107], v[0:3]
	v_mfma_f32_16x16x32_bf16 v[52:55], v[100:103], v[108:111], v[52:55]
	v_mfma_f32_16x16x32_bf16 v[44:47], v[100:103], v[112:115], v[44:47]
	s_cbranch_scc0 .LBB0_2314
;   DI u32x2 pack(int, int, float a, float b, float c, float d, float&) const { u32x2 v; v.x = pack2(a, b); v.y = pack2(c, d); return v; }
; template <class ARow, class Epi>
; DI void gemm_tile(const ARow& arow, long a_kstride, const u16* __restrict__ Bt, long ldb, int K, int m0, int n0,
;                   const Epi& epi, char* smem) {
;     ...
;     for (int ks = 0; ks < 2; ++ks) {
;       bf16x8 wf[4], af[4];
; #pragma unroll
;       for (int j = 0; j < 4; ++j) {
;         wf[j] = *(const bf16x8*)(sb + j * 2048 + foff[ks]);
;         af[j] = *(const bf16x8*)(sa + j * 2048 + foff[ks]);
;       }
; #pragma unroll
;       for (int ni = 0; ni < 4; ++ni)
; #pragma unroll
;         for (int mi = 0; mi < 4; ++mi) acc[ni][mi] = __builtin_amdgcn_mfma_f32_16x16x32_bf16(wf[ni], af[mi], acc[ni][mi], 0, 0, 0);
;     }
;     asm volatile("s_waitcnt vmcnt(0)" ::: "memory");
;     __syncthreads();
;   }
;     ...
;   const int nh = n0 + wn * 64;
;   if (epi.packed(nh)) {
; #pragma unroll
;     for (int mi = 0; mi < 4; ++mi) {
;       const int m = m0 + wm * 64 + mi * 16 + fr;
;       float ss = 0.f;
;       u32x2 pk[4];
; #pragma unroll
;       for (int ni = 0; ni < 4; ++ni) pk[ni] = epi.pack(m, nh + ni * 16 + fq * 4, acc[ni][mi][0], acc[ni][mi][1], acc[ni][mi][2], acc[ni][mi][3], ss);
;       epi.finish16(m, nh, ss);
;       u16* rp = epi.rowp(m) + nh;
; #pragma unroll
;       for (int pp = 0; pp < 2; ++pp) {
;         u32x2 a = pk[2 * pp], b = pk[2 * pp + 1];
;         const u32x2 rx = __builtin_amdgcn_permlane16_swap(a.x, b.x, false, false);
;         const u32x2 ry = __builtin_amdgcn_permlane16_swap(a.y, b.y, false, false);
;         const int nst = (fq & 1) ? ((2 * pp + 1) * 16 + (fq - 1) * 4) : ((2 * pp) * 16 + fq * 4);
;         *(u32x4*)(rp + nst) = (u32x4){rx[0], ry[0], rx[1], ry[1]};
;       }
	v_add_u32_e32 v106, v89, v87
	ds_read_b128 v[66:69], v106 offset:49152
	v_add_u32_e32 v87, v88, v87
	ds_read_b128 v[70:73], v87 offset:32768
	ds_read_b128 v[74:77], v87 offset:34816
	ds_read_b128 v[78:81], v87 offset:36864
	ds_read_b128 v[90:93], v87 offset:38912
	v_add_u32_e32 v114, v89, v86
	s_waitcnt lgkmcnt(3)
	v_mfma_f32_16x16x32_bf16 v[60:63], v[66:69], v[70:73], v[60:63]
	s_waitcnt lgkmcnt(2)
	v_mfma_f32_16x16x32_bf16 v[56:59], v[66:69], v[74:77], v[56:59]
	s_waitcnt lgkmcnt(1)
	v_mfma_f32_16x16x32_bf16 v[48:51], v[66:69], v[78:81], v[48:51]
	s_waitcnt lgkmcnt(0)
	v_mfma_f32_16x16x32_bf16 v[40:43], v[66:69], v[90:93], v[40:43]
	ds_read_b128 v[66:69], v106 offset:51200
	s_waitcnt lgkmcnt(0)
	v_mfma_f32_16x16x32_bf16 v[36:39], v[66:69], v[70:73], v[36:39]
	v_mfma_f32_16x16x32_bf16 v[32:35], v[66:69], v[74:77], v[32:35]
	v_mfma_f32_16x16x32_bf16 v[94:97], v[66:69], v[78:81], v[28:31]
	v_mfma_f32_16x16x32_bf16 v[66:69], v[66:69], v[90:93], v[24:27]
	s_nop 2
	ds_read_b128 v[24:27], v106 offset:53248
	s_waitcnt lgkmcnt(0)
	v_mfma_f32_16x16x32_bf16 v[102:105], v[24:27], v[90:93], v[8:11]
	s_nop 2
	ds_read_b128 v[8:11], v106 offset:55296
	v_mfma_f32_16x16x32_bf16 v[20:23], v[24:27], v[70:73], v[20:23]
	s_waitcnt lgkmcnt(0)
	v_mfma_f32_16x16x32_bf16 v[70:73], v[8:11], v[70:73], v[4:7]
	s_nop 2
	ds_read_b128 v[4:7], v114 offset:49152
	v_mfma_f32_16x16x32_bf16 v[98:101], v[24:27], v[78:81], v[12:15]
	s_nop 2
	v_add_u32_e32 v12, v88, v86
	v_mfma_f32_16x16x32_bf16 v[16:19], v[24:27], v[74:77], v[16:19]
	ds_read_b128 v[86:89], v12 offset:32768
	ds_read_b128 v[106:109], v12 offset:36864
	ds_read_b128 v[110:113], v12 offset:38912
	v_mfma_f32_16x16x32_bf16 v[0:3], v[8:11], v[74:77], v[0:3]
	v_mfma_f32_16x16x32_bf16 v[74:77], v[8:11], v[78:81], v[52:55]
	v_mfma_f32_16x16x32_bf16 v[78:81], v[8:11], v[90:93], v[44:47]
	ds_read_b128 v[90:93], v12 offset:34816
	s_waitcnt lgkmcnt(3)
	v_mfma_f32_16x16x32_bf16 v[60:63], v[4:7], v[86:89], v[60:63]
	s_waitcnt lgkmcnt(0)
	v_mfma_f32_16x16x32_bf16 v[44:47], v[4:7], v[90:93], v[56:59]
	v_mfma_f32_16x16x32_bf16 v[28:31], v[4:7], v[106:109], v[48:51]
	v_mfma_f32_16x16x32_bf16 v[12:15], v[4:7], v[110:113], v[40:43]
	ds_read_b128 v[4:7], v114 offset:51200
	s_waitcnt lgkmcnt(0)
	v_mfma_f32_16x16x32_bf16 v[56:59], v[4:7], v[86:89], v[36:39]
	v_mfma_f32_16x16x32_bf16 v[40:43], v[4:7], v[90:93], v[32:35]
	v_mfma_f32_16x16x32_bf16 v[24:27], v[4:7], v[106:109], v[94:97]
	v_mfma_f32_16x16x32_bf16 v[8:11], v[4:7], v[110:113], v[66:69]
	ds_read_b128 v[4:7], v114 offset:53248
	s_nop 0
	ds_read_b128 v[94:97], v114 offset:55296
	s_waitcnt lgkmcnt(0)
	s_waitcnt vmcnt(0)
	s_waitcnt lgkmcnt(0)
	v_mfma_f32_16x16x32_bf16 v[32:35], v[94:97], v[90:93], v[0:3]
	s_nop 2
	v_or_b32_e32 v0, s0, v64
	v_lshl_add_u32 v66, v85, 6, v0
	v_lshl_or_b32 v68, v84, 6, s34
	v_mfma_f32_16x16x32_bf16 v[52:55], v[4:7], v[86:89], v[20:23]
	v_cmp_lt_i32_e32 vcc, s30, v68
	s_barrier
	v_mfma_f32_16x16x32_bf16 v[36:39], v[4:7], v[90:93], v[16:19]
	v_mfma_f32_16x16x32_bf16 v[20:23], v[4:7], v[106:109], v[98:101]
	v_mfma_f32_16x16x32_bf16 v[4:7], v[4:7], v[110:113], v[102:105]
	v_mfma_f32_16x16x32_bf16 v[48:51], v[94:97], v[86:89], v[70:73]
	v_mfma_f32_16x16x32_bf16 v[16:19], v[94:97], v[106:109], v[74:77]
	s_nop 1
	v_lshlrev_b32_e32 v70, 2, v83
	v_or_b32_e32 v64, v68, v70
	v_mfma_f32_16x16x32_bf16 v[0:3], v[94:97], v[110:113], v[78:81]
	s_nop 7
	v_readfirstlane_b32 s99, v68
	s_cmpk_ge_u32 s99, 0x400
	s_cbranch_scc0 .Lfe_D_not_plain
	s_cmpk_lt_u32 s99, 0xc00
	s_cbranch_scc0 .Lfe_D_not_plain
	s_load_dwordx2 s[100:101], s[56:57], 0x130
	v_and_b32_e32 v152, 1, v83
	v_mul_u32_u24_e32 v152, 12, v152
	v_lshl_add_u32 v152, v83, 2, v152
	v_add_u32_e32 v152, v152, v68
	v_lshl_add_u32 v152, v66, 12, v152
	v_lshlrev_b32_e32 v152, 1, v152
	v_add_u32_e32 v153, 0x20000, v152
	v_add_u32_e32 v154, 0x40000, v152
	v_add_u32_e32 v155, 0x60000, v152
	s_nop 3
	v_cvt_pk_bf16_f32 v120, v60, v61
	v_cvt_pk_bf16_f32 v121, v62, v63
	v_cvt_pk_bf16_f32 v122, v56, v57
	v_cvt_pk_bf16_f32 v123, v58, v59
	v_cvt_pk_bf16_f32 v124, v52, v53
	v_cvt_pk_bf16_f32 v125, v54, v55
	v_cvt_pk_bf16_f32 v126, v48, v49
	v_cvt_pk_bf16_f32 v127, v50, v51
	s_nop 1
	v_permlane16_swap_b32_e32 v120, v122
	v_permlane16_swap_b32_e32 v121, v123
	v_permlane16_swap_b32_e32 v124, v126
	v_permlane16_swap_b32_e32 v125, v127
	s_waitcnt lgkmcnt(0)
	global_store_dwordx4 v152, v[120:123], s[100:101]
	global_store_dwordx4 v152, v[124:127], s[100:101] offset:64
	v_cvt_pk_bf16_f32 v128, v44, v45
	v_cvt_pk_bf16_f32 v129, v46, v47
	v_cvt_pk_bf16_f32 v130, v40, v41
	v_cvt_pk_bf16_f32 v131, v42, v43
	v_cvt_pk_bf16_f32 v132, v36, v37
	v_cvt_pk_bf16_f32 v133, v38, v39
	v_cvt_pk_bf16_f32 v134, v32, v33
	v_cvt_pk_bf16_f32 v135, v34, v35
	s_nop 1
	v_permlane16_swap_b32_e32 v128, v130
	v_permlane16_swap_b32_e32 v129, v131
	v_permlane16_swap_b32_e32 v132, v134
	v_permlane16_swap_b32_e32 v133, v135
	global_store_dwordx4 v153, v[128:131], s[100:101]
	global_store_dwordx4 v153, v[132:135], s[100:101] offset:64
	v_cvt_pk_bf16_f32 v136, v28, v29
	v_cvt_pk_bf16_f32 v137, v30, v31
	v_cvt_pk_bf16_f32 v138, v24, v25
	v_cvt_pk_bf16_f32 v139, v26, v27
	v_cvt_pk_bf16_f32 v140, v20, v21
	v_cvt_pk_bf16_f32 v141, v22, v23
	v_cvt_pk_bf16_f32 v142, v16, v17
	v_cvt_pk_bf16_f32 v143, v18, v19
	s_nop 1
	v_permlane16_swap_b32_e32 v136, v138
	v_permlane16_swap_b32_e32 v137, v139
	v_permlane16_swap_b32_e32 v140, v142
	v_permlane16_swap_b32_e32 v141, v143
	global_store_dwordx4 v154, v[136:139], s[100:101]
	global_store_dwordx4 v154, v[140:143], s[100:101] offset:64
	v_cvt_pk_bf16_f32 v144, v12, v13
	v_cvt_pk_bf16_f32 v145, v14, v15
	v_cvt_pk_bf16_f32 v146, v8, v9
	v_cvt_pk_bf16_f32 v147, v10, v11
	v_cvt_pk_bf16_f32 v148, v4, v5
	v_cvt_pk_bf16_f32 v149, v6, v7
	v_cvt_pk_bf16_f32 v150, v0, v1
	v_cvt_pk_bf16_f32 v151, v2, v3
	s_nop 1
	v_permlane16_swap_b32_e32 v144, v146
	v_permlane16_swap_b32_e32 v145, v147
	v_permlane16_swap_b32_e32 v148, v150
	v_permlane16_swap_b32_e32 v149, v151
	global_store_dwordx4 v155, v[144:147], s[100:101]
	global_store_dwordx4 v155, v[148:151], s[100:101] offset:64
	s_branch .Lfe_join_D
